# v43 + store-drain cover v2: next unit's first two LDS-DMA requests issued at the epilogue start before its stores; three load segments peeled with vmcnt(8+S) (G1, F1, F1')
# baseline (speedup 1.0000x reference)
.LBB0_393:
	s_ashr_i32 s19, s18, 31
	s_lshl_b64 s[0:1], s[18:19], 20
	s_add_u32 s20, s42, s0
	s_addc_u32 s21, s43, s1
	s_and_b64 s[0:1], s[4:5], exec
	s_cselect_b32 s7, s21, s25
	s_cselect_b32 s19, s20, s24
	s_ashr_i32 s17, s16, 31
	s_lshl_b64 s[0:1], s[16:17], 20
	s_add_u32 s22, s30, s0
	s_addc_u32 s23, s31, s1
	s_and_b64 s[0:1], s[4:5], exec
	s_cselect_b32 s17, s23, s27
	s_cselect_b32 s49, s22, s26
	s_add_u32 s24, s24, 0x80080
	s_addc_u32 s25, s25, 0
	s_add_u32 s58, s26, 0x100
	v_mov_b32_e32 v2, 0
	s_addc_u32 s59, s27, 0
	s_mov_b32 s60, -2
	v_mov_b32_e32 v3, v2
	s_waitcnt lgkmcnt(0)
	v_pk_mov_b32 v[4:5], v[2:3], v[2:3] op_sel:[0,1]
	v_pk_mov_b32 v[6:7], v[2:3], v[2:3] op_sel:[0,1]
	v_pk_mov_b32 v[8:9], v[2:3], v[2:3] op_sel:[0,1]
	v_pk_mov_b32 v[18:19], v[2:3], v[2:3] op_sel:[0,1]
	v_pk_mov_b32 v[20:21], v[2:3], v[2:3] op_sel:[0,1]
	v_pk_mov_b32 v[22:23], v[2:3], v[2:3] op_sel:[0,1]
	v_pk_mov_b32 v[24:25], v[2:3], v[2:3] op_sel:[0,1]
	v_pk_mov_b32 v[34:35], v[2:3], v[2:3] op_sel:[0,1]
	v_pk_mov_b32 v[36:37], v[2:3], v[2:3] op_sel:[0,1]
	v_pk_mov_b32 v[38:39], v[2:3], v[2:3] op_sel:[0,1]
	v_pk_mov_b32 v[40:41], v[2:3], v[2:3] op_sel:[0,1]
	v_pk_mov_b32 v[50:51], v[2:3], v[2:3] op_sel:[0,1]
	v_pk_mov_b32 v[52:53], v[2:3], v[2:3] op_sel:[0,1]
	v_pk_mov_b32 v[54:55], v[2:3], v[2:3] op_sel:[0,1]
	v_pk_mov_b32 v[56:57], v[2:3], v[2:3] op_sel:[0,1]
	v_pk_mov_b32 v[10:11], v[2:3], v[2:3] op_sel:[0,1]
	v_pk_mov_b32 v[12:13], v[2:3], v[2:3] op_sel:[0,1]
	v_pk_mov_b32 v[14:15], v[2:3], v[2:3] op_sel:[0,1]
	v_pk_mov_b32 v[16:17], v[2:3], v[2:3] op_sel:[0,1]
	v_pk_mov_b32 v[26:27], v[2:3], v[2:3] op_sel:[0,1]
	v_pk_mov_b32 v[28:29], v[2:3], v[2:3] op_sel:[0,1]
	v_pk_mov_b32 v[30:31], v[2:3], v[2:3] op_sel:[0,1]
	v_pk_mov_b32 v[32:33], v[2:3], v[2:3] op_sel:[0,1]
	v_pk_mov_b32 v[42:43], v[2:3], v[2:3] op_sel:[0,1]
	v_pk_mov_b32 v[44:45], v[2:3], v[2:3] op_sel:[0,1]
	v_pk_mov_b32 v[46:47], v[2:3], v[2:3] op_sel:[0,1]
	v_pk_mov_b32 v[48:49], v[2:3], v[2:3] op_sel:[0,1]
	v_pk_mov_b32 v[58:59], v[2:3], v[2:3] op_sel:[0,1]
	v_pk_mov_b32 v[60:61], v[2:3], v[2:3] op_sel:[0,1]
	v_pk_mov_b32 v[62:63], v[2:3], v[2:3] op_sel:[0,1]
	v_pk_mov_b32 v[64:65], v[2:3], v[2:3] op_sel:[0,1]
	v_pk_mov_b32 v[66:67], v[2:3], v[2:3] op_sel:[0,1]
	v_pk_mov_b32 v[68:69], v[2:3], v[2:3] op_sel:[0,1]
	v_pk_mov_b32 v[70:71], v[2:3], v[2:3] op_sel:[0,1]
	v_pk_mov_b32 v[72:73], v[2:3], v[2:3] op_sel:[0,1]
	v_pk_mov_b32 v[82:83], v[2:3], v[2:3] op_sel:[0,1]
	v_pk_mov_b32 v[84:85], v[2:3], v[2:3] op_sel:[0,1]
	v_pk_mov_b32 v[86:87], v[2:3], v[2:3] op_sel:[0,1]
	v_pk_mov_b32 v[88:89], v[2:3], v[2:3] op_sel:[0,1]
	v_pk_mov_b32 v[98:99], v[2:3], v[2:3] op_sel:[0,1]
	v_pk_mov_b32 v[100:101], v[2:3], v[2:3] op_sel:[0,1]
	v_pk_mov_b32 v[102:103], v[2:3], v[2:3] op_sel:[0,1]
	v_pk_mov_b32 v[104:105], v[2:3], v[2:3] op_sel:[0,1]
	v_pk_mov_b32 v[114:115], v[2:3], v[2:3] op_sel:[0,1]
	v_pk_mov_b32 v[116:117], v[2:3], v[2:3] op_sel:[0,1]
	v_pk_mov_b32 v[118:119], v[2:3], v[2:3] op_sel:[0,1]
	v_pk_mov_b32 v[120:121], v[2:3], v[2:3] op_sel:[0,1]
	v_pk_mov_b32 v[74:75], v[2:3], v[2:3] op_sel:[0,1]
	v_pk_mov_b32 v[76:77], v[2:3], v[2:3] op_sel:[0,1]
	v_pk_mov_b32 v[78:79], v[2:3], v[2:3] op_sel:[0,1]
	v_pk_mov_b32 v[80:81], v[2:3], v[2:3] op_sel:[0,1]
	v_pk_mov_b32 v[90:91], v[2:3], v[2:3] op_sel:[0,1]
	v_pk_mov_b32 v[92:93], v[2:3], v[2:3] op_sel:[0,1]
	v_pk_mov_b32 v[94:95], v[2:3], v[2:3] op_sel:[0,1]
	v_pk_mov_b32 v[96:97], v[2:3], v[2:3] op_sel:[0,1]
	v_pk_mov_b32 v[106:107], v[2:3], v[2:3] op_sel:[0,1]
	v_pk_mov_b32 v[108:109], v[2:3], v[2:3] op_sel:[0,1]
	v_pk_mov_b32 v[110:111], v[2:3], v[2:3] op_sel:[0,1]
	v_pk_mov_b32 v[112:113], v[2:3], v[2:3] op_sel:[0,1]
	v_pk_mov_b32 v[122:123], v[2:3], v[2:3] op_sel:[0,1]
	v_pk_mov_b32 v[124:125], v[2:3], v[2:3] op_sel:[0,1]
	v_pk_mov_b32 v[126:127], v[2:3], v[2:3] op_sel:[0,1]
	v_pk_mov_b32 v[128:129], v[2:3], v[2:3] op_sel:[0,1]
	s_cmp_eq_u32 s101, 0x80000001
	s_cbranch_scc0 .LBB0_394
	s_add_u32 s0, s24, 0xfff80080
	s_addc_u32 s1, s25, -1
	s_add_i32 s33, 0, 0x10000
	s_cmp_eq_u32 s60, 28
	s_cselect_b32 s29, s7, s1
	s_cselect_b32 s28, s19, s0
	s_cselect_b32 s27, s17, s59
	s_cselect_b32 s26, s49, s58
	s_add_i32 s55, 0, 0x14000
	ds_read_b128 v[142:145], v151
	ds_read_b128 v[146:149], v151 offset:1024
	ds_read_b128 v[154:157], v151 offset:2048
	ds_read_b128 v[158:161], v151 offset:3072
	ds_read_b128 v[162:165], v151 offset:16384
	ds_read_b128 v[166:169], v151 offset:17408
	ds_read_b128 v[170:173], v151 offset:18432
	ds_read_b128 v[174:177], v151 offset:19456
	s_add_i32 m0, s9, 0xc000
	ds_read_b128 v[178:181], v153
	ds_read_b128 v[182:185], v153 offset:1024
	ds_read_b128 v[186:189], v153 offset:2048
	ds_read_b128 v[190:193], v153 offset:3072
	ds_read_b128 v[194:197], v153 offset:4096
	ds_read_b128 v[198:201], v153 offset:5120
	ds_read_b128 v[208:211], v153 offset:6144
	ds_read_b128 v[212:215], v153 offset:7168
	s_add_i32 m0, s9, 0xe000
	s_nop 0
	s_waitcnt vmcnt(24)
	s_waitcnt lgkmcnt(0)
	s_setprio 1
	s_barrier
	v_mfma_f32_16x16x32_bf16 v[126:129], v[142:145], v[178:181], v[126:129]
	v_mfma_f32_16x16x32_bf16 v[122:125], v[154:157], v[178:181], v[122:125]
	v_mfma_f32_16x16x32_bf16 v[110:113], v[142:145], v[186:189], v[110:113]
	v_mfma_f32_16x16x32_bf16 v[106:109], v[154:157], v[186:189], v[106:109]
	v_mfma_f32_16x16x32_bf16 v[94:97], v[142:145], v[194:197], v[94:97]
	v_mfma_f32_16x16x32_bf16 v[90:93], v[154:157], v[194:197], v[90:93]
	v_mfma_f32_16x16x32_bf16 v[78:81], v[142:145], v[208:211], v[78:81]
	v_mfma_f32_16x16x32_bf16 v[74:77], v[154:157], v[208:211], v[74:77]
	v_mfma_f32_16x16x32_bf16 v[126:129], v[146:149], v[182:185], v[126:129]
	v_mfma_f32_16x16x32_bf16 v[122:125], v[158:161], v[182:185], v[122:125]
	v_mfma_f32_16x16x32_bf16 v[110:113], v[146:149], v[190:193], v[110:113]
	v_mfma_f32_16x16x32_bf16 v[106:109], v[158:161], v[190:193], v[106:109]
	v_mfma_f32_16x16x32_bf16 v[94:97], v[146:149], v[198:201], v[94:97]
	v_mfma_f32_16x16x32_bf16 v[90:93], v[158:161], v[198:201], v[90:93]
	v_mfma_f32_16x16x32_bf16 v[78:81], v[146:149], v[212:215], v[78:81]
	v_mfma_f32_16x16x32_bf16 v[74:77], v[158:161], v[212:215], v[74:77]
	v_mfma_f32_16x16x32_bf16 v[118:121], v[162:165], v[178:181], v[118:121]
	v_mfma_f32_16x16x32_bf16 v[114:117], v[170:173], v[178:181], v[114:117]
	v_mfma_f32_16x16x32_bf16 v[102:105], v[162:165], v[186:189], v[102:105]
	v_mfma_f32_16x16x32_bf16 v[98:101], v[170:173], v[186:189], v[98:101]
	v_mfma_f32_16x16x32_bf16 v[86:89], v[162:165], v[194:197], v[86:89]
	v_mfma_f32_16x16x32_bf16 v[82:85], v[170:173], v[194:197], v[82:85]
	v_mfma_f32_16x16x32_bf16 v[70:73], v[162:165], v[208:211], v[70:73]
	v_mfma_f32_16x16x32_bf16 v[66:69], v[170:173], v[208:211], v[66:69]
	v_mfma_f32_16x16x32_bf16 v[118:121], v[166:169], v[182:185], v[118:121]
	v_mfma_f32_16x16x32_bf16 v[114:117], v[174:177], v[182:185], v[114:117]
	v_mfma_f32_16x16x32_bf16 v[102:105], v[166:169], v[190:193], v[102:105]
	v_mfma_f32_16x16x32_bf16 v[98:101], v[174:177], v[190:193], v[98:101]
	v_mfma_f32_16x16x32_bf16 v[86:89], v[166:169], v[198:201], v[86:89]
	v_mfma_f32_16x16x32_bf16 v[82:85], v[174:177], v[198:201], v[82:85]
	v_mfma_f32_16x16x32_bf16 v[70:73], v[166:169], v[212:215], v[70:73]
	v_mfma_f32_16x16x32_bf16 v[66:69], v[174:177], v[212:215], v[66:69]
	s_barrier
	s_setprio 0
	s_add_i32 s0, s33, s34
	s_mov_b32 m0, s0
	ds_read_b128 v[178:181], v153 offset:16384
	ds_read_b128 v[182:185], v153 offset:17408
	ds_read_b128 v[186:189], v153 offset:18432
	ds_read_b128 v[190:193], v153 offset:19456
	ds_read_b128 v[194:197], v153 offset:20480
	ds_read_b128 v[198:201], v153 offset:21504
	ds_read_b128 v[208:211], v153 offset:22528
	ds_read_b128 v[212:215], v153 offset:23552
	global_load_lds_dwordx4 v132, s[26:27]
	s_add_i32 m0, s0, 0x2000
	s_add_u32 s0, s26, 0x80000
	s_addc_u32 s1, s27, 0
	s_add_i32 s33, s55, s34
	global_load_lds_dwordx4 v136, s[26:27]
	s_mov_b32 m0, s33
	s_nop 0
	global_load_lds_dwordx4 v132, s[0:1]
	s_add_i32 m0, s33, 0x2000
	s_nop 0
	global_load_lds_dwordx4 v136, s[0:1]
	s_mov_b32 m0, s9
	s_nop 0
	global_load_lds_dwordx4 v130, s[28:29]
	s_mov_b32 m0, s35
	s_nop 0
	global_load_lds_dwordx4 v134, s[28:29]
	s_waitcnt vmcnt(24)
	s_waitcnt lgkmcnt(0)
	s_setprio 1
	s_barrier
	v_mfma_f32_16x16x32_bf16 v[62:65], v[142:145], v[178:181], v[62:65]
	v_mfma_f32_16x16x32_bf16 v[58:61], v[154:157], v[178:181], v[58:61]
	v_mfma_f32_16x16x32_bf16 v[46:49], v[142:145], v[186:189], v[46:49]
	v_mfma_f32_16x16x32_bf16 v[42:45], v[154:157], v[186:189], v[42:45]
	v_mfma_f32_16x16x32_bf16 v[30:33], v[142:145], v[194:197], v[30:33]
	v_mfma_f32_16x16x32_bf16 v[26:29], v[154:157], v[194:197], v[26:29]
	v_mfma_f32_16x16x32_bf16 v[14:17], v[142:145], v[208:211], v[14:17]
	v_mfma_f32_16x16x32_bf16 v[10:13], v[154:157], v[208:211], v[10:13]
	v_mfma_f32_16x16x32_bf16 v[62:65], v[146:149], v[182:185], v[62:65]
	v_mfma_f32_16x16x32_bf16 v[58:61], v[158:161], v[182:185], v[58:61]
	v_mfma_f32_16x16x32_bf16 v[46:49], v[146:149], v[190:193], v[46:49]
	v_mfma_f32_16x16x32_bf16 v[42:45], v[158:161], v[190:193], v[42:45]
	v_mfma_f32_16x16x32_bf16 v[30:33], v[146:149], v[198:201], v[30:33]
	v_mfma_f32_16x16x32_bf16 v[26:29], v[158:161], v[198:201], v[26:29]
	v_mfma_f32_16x16x32_bf16 v[14:17], v[146:149], v[212:215], v[14:17]
	v_mfma_f32_16x16x32_bf16 v[10:13], v[158:161], v[212:215], v[10:13]
	v_mfma_f32_16x16x32_bf16 v[54:57], v[162:165], v[178:181], v[54:57]
	v_mfma_f32_16x16x32_bf16 v[50:53], v[170:173], v[178:181], v[50:53]
	v_mfma_f32_16x16x32_bf16 v[38:41], v[162:165], v[186:189], v[38:41]
	v_mfma_f32_16x16x32_bf16 v[34:37], v[170:173], v[186:189], v[34:37]
	v_mfma_f32_16x16x32_bf16 v[22:25], v[162:165], v[194:197], v[22:25]
	v_mfma_f32_16x16x32_bf16 v[18:21], v[170:173], v[194:197], v[18:21]
	v_mfma_f32_16x16x32_bf16 v[6:9], v[162:165], v[208:211], v[6:9]
	v_mfma_f32_16x16x32_bf16 v[2:5], v[170:173], v[208:211], v[2:5]
	v_mfma_f32_16x16x32_bf16 v[54:57], v[166:169], v[182:185], v[54:57]
	v_mfma_f32_16x16x32_bf16 v[50:53], v[174:177], v[182:185], v[50:53]
	v_mfma_f32_16x16x32_bf16 v[38:41], v[166:169], v[190:193], v[38:41]
	v_mfma_f32_16x16x32_bf16 v[34:37], v[174:177], v[190:193], v[34:37]
	v_mfma_f32_16x16x32_bf16 v[22:25], v[166:169], v[198:201], v[22:25]
	v_mfma_f32_16x16x32_bf16 v[18:21], v[174:177], v[198:201], v[18:21]
	v_mfma_f32_16x16x32_bf16 v[6:9], v[166:169], v[212:215], v[6:9]
	v_mfma_f32_16x16x32_bf16 v[2:5], v[174:177], v[212:215], v[2:5]
	s_barrier
	s_setprio 0
	s_add_i32 s33, 0, 0x18000
	s_add_i32 s55, 0, 0x1c000
	ds_read_b128 v[142:145], v151 offset:32768
	ds_read_b128 v[146:149], v151 offset:33792
	ds_read_b128 v[154:157], v151 offset:34816
	ds_read_b128 v[158:161], v151 offset:35840
	ds_read_b128 v[162:165], v151 offset:49152
	ds_read_b128 v[166:169], v151 offset:50176
	ds_read_b128 v[170:173], v151 offset:51200
	ds_read_b128 v[174:177], v151 offset:52224
	s_add_u32 s0, s28, 0x80000
	s_addc_u32 s1, s29, 0
	s_mov_b32 m0, s36
	ds_read_b128 v[178:181], v153 offset:32768
	ds_read_b128 v[182:185], v153 offset:33792
	ds_read_b128 v[186:189], v153 offset:34816
	ds_read_b128 v[190:193], v153 offset:35840
	ds_read_b128 v[194:197], v153 offset:36864
	ds_read_b128 v[198:201], v153 offset:37888
	ds_read_b128 v[208:211], v153 offset:38912
	ds_read_b128 v[212:215], v153 offset:39936
	global_load_lds_dwordx4 v130, s[0:1]
	s_mov_b32 m0, s37
	s_nop 0
	global_load_lds_dwordx4 v134, s[0:1]
	s_waitcnt vmcnt(24)
	s_waitcnt lgkmcnt(0)
	s_setprio 1
	s_barrier
	v_mfma_f32_16x16x32_bf16 v[126:129], v[142:145], v[178:181], v[126:129]
	v_mfma_f32_16x16x32_bf16 v[122:125], v[154:157], v[178:181], v[122:125]
	v_mfma_f32_16x16x32_bf16 v[110:113], v[142:145], v[186:189], v[110:113]
	v_mfma_f32_16x16x32_bf16 v[106:109], v[154:157], v[186:189], v[106:109]
	v_mfma_f32_16x16x32_bf16 v[94:97], v[142:145], v[194:197], v[94:97]
	v_mfma_f32_16x16x32_bf16 v[90:93], v[154:157], v[194:197], v[90:93]
	v_mfma_f32_16x16x32_bf16 v[78:81], v[142:145], v[208:211], v[78:81]
	v_mfma_f32_16x16x32_bf16 v[74:77], v[154:157], v[208:211], v[74:77]
	v_mfma_f32_16x16x32_bf16 v[126:129], v[146:149], v[182:185], v[126:129]
	v_mfma_f32_16x16x32_bf16 v[122:125], v[158:161], v[182:185], v[122:125]
	v_mfma_f32_16x16x32_bf16 v[110:113], v[146:149], v[190:193], v[110:113]
	v_mfma_f32_16x16x32_bf16 v[106:109], v[158:161], v[190:193], v[106:109]
	v_mfma_f32_16x16x32_bf16 v[94:97], v[146:149], v[198:201], v[94:97]
	v_mfma_f32_16x16x32_bf16 v[90:93], v[158:161], v[198:201], v[90:93]
	v_mfma_f32_16x16x32_bf16 v[78:81], v[146:149], v[212:215], v[78:81]
	v_mfma_f32_16x16x32_bf16 v[74:77], v[158:161], v[212:215], v[74:77]
	v_mfma_f32_16x16x32_bf16 v[118:121], v[162:165], v[178:181], v[118:121]
	v_mfma_f32_16x16x32_bf16 v[114:117], v[170:173], v[178:181], v[114:117]
	v_mfma_f32_16x16x32_bf16 v[102:105], v[162:165], v[186:189], v[102:105]
	v_mfma_f32_16x16x32_bf16 v[98:101], v[170:173], v[186:189], v[98:101]
	v_mfma_f32_16x16x32_bf16 v[86:89], v[162:165], v[194:197], v[86:89]
	v_mfma_f32_16x16x32_bf16 v[82:85], v[170:173], v[194:197], v[82:85]
	v_mfma_f32_16x16x32_bf16 v[70:73], v[162:165], v[208:211], v[70:73]
	v_mfma_f32_16x16x32_bf16 v[66:69], v[170:173], v[208:211], v[66:69]
	v_mfma_f32_16x16x32_bf16 v[118:121], v[166:169], v[182:185], v[118:121]
	v_mfma_f32_16x16x32_bf16 v[114:117], v[174:177], v[182:185], v[114:117]
	v_mfma_f32_16x16x32_bf16 v[102:105], v[166:169], v[190:193], v[102:105]
	v_mfma_f32_16x16x32_bf16 v[98:101], v[174:177], v[190:193], v[98:101]
	v_mfma_f32_16x16x32_bf16 v[86:89], v[166:169], v[198:201], v[86:89]
	v_mfma_f32_16x16x32_bf16 v[82:85], v[174:177], v[198:201], v[82:85]
	v_mfma_f32_16x16x32_bf16 v[70:73], v[166:169], v[212:215], v[70:73]
	v_mfma_f32_16x16x32_bf16 v[66:69], v[174:177], v[212:215], v[66:69]
	s_barrier
	s_setprio 0
	s_branch .Lpeel_mid_0
.LBB0_394:
	s_add_u32 s0, s24, 0xfff80080
	s_addc_u32 s1, s25, -1
	s_add_i32 s33, 0, 0x10000
	s_cmp_eq_u32 s60, 28
	s_cselect_b32 s29, s7, s1
	s_cselect_b32 s28, s19, s0
	s_cselect_b32 s27, s17, s59
	s_cselect_b32 s26, s49, s58
	s_add_i32 s55, 0, 0x14000
	ds_read_b128 v[142:145], v151
	ds_read_b128 v[146:149], v151 offset:1024
	ds_read_b128 v[154:157], v151 offset:2048
	ds_read_b128 v[158:161], v151 offset:3072
	ds_read_b128 v[162:165], v151 offset:16384
	ds_read_b128 v[166:169], v151 offset:17408
	ds_read_b128 v[170:173], v151 offset:18432
	ds_read_b128 v[174:177], v151 offset:19456
	s_add_i32 m0, s9, 0xc000
	ds_read_b128 v[178:181], v153
	ds_read_b128 v[182:185], v153 offset:1024
	ds_read_b128 v[186:189], v153 offset:2048
	ds_read_b128 v[190:193], v153 offset:3072
	ds_read_b128 v[194:197], v153 offset:4096
	ds_read_b128 v[198:201], v153 offset:5120
	ds_read_b128 v[208:211], v153 offset:6144
	ds_read_b128 v[212:215], v153 offset:7168
	global_load_lds_dwordx4 v138, s[24:25]
	s_add_i32 m0, s9, 0xe000
	s_nop 0
	global_load_lds_dwordx4 v140, s[24:25]
	s_waitcnt vmcnt(8)
	s_waitcnt lgkmcnt(0)
	s_setprio 1
	s_barrier
	v_mfma_f32_16x16x32_bf16 v[126:129], v[142:145], v[178:181], v[126:129]
	v_mfma_f32_16x16x32_bf16 v[122:125], v[154:157], v[178:181], v[122:125]
	v_mfma_f32_16x16x32_bf16 v[110:113], v[142:145], v[186:189], v[110:113]
	v_mfma_f32_16x16x32_bf16 v[106:109], v[154:157], v[186:189], v[106:109]
	v_mfma_f32_16x16x32_bf16 v[94:97], v[142:145], v[194:197], v[94:97]
	v_mfma_f32_16x16x32_bf16 v[90:93], v[154:157], v[194:197], v[90:93]
	v_mfma_f32_16x16x32_bf16 v[78:81], v[142:145], v[208:211], v[78:81]
	v_mfma_f32_16x16x32_bf16 v[74:77], v[154:157], v[208:211], v[74:77]
	v_mfma_f32_16x16x32_bf16 v[126:129], v[146:149], v[182:185], v[126:129]
	v_mfma_f32_16x16x32_bf16 v[122:125], v[158:161], v[182:185], v[122:125]
	v_mfma_f32_16x16x32_bf16 v[110:113], v[146:149], v[190:193], v[110:113]
	v_mfma_f32_16x16x32_bf16 v[106:109], v[158:161], v[190:193], v[106:109]
	v_mfma_f32_16x16x32_bf16 v[94:97], v[146:149], v[198:201], v[94:97]
	v_mfma_f32_16x16x32_bf16 v[90:93], v[158:161], v[198:201], v[90:93]
	v_mfma_f32_16x16x32_bf16 v[78:81], v[146:149], v[212:215], v[78:81]
	v_mfma_f32_16x16x32_bf16 v[74:77], v[158:161], v[212:215], v[74:77]
	v_mfma_f32_16x16x32_bf16 v[118:121], v[162:165], v[178:181], v[118:121]
	v_mfma_f32_16x16x32_bf16 v[114:117], v[170:173], v[178:181], v[114:117]
	v_mfma_f32_16x16x32_bf16 v[102:105], v[162:165], v[186:189], v[102:105]
	v_mfma_f32_16x16x32_bf16 v[98:101], v[170:173], v[186:189], v[98:101]
	v_mfma_f32_16x16x32_bf16 v[86:89], v[162:165], v[194:197], v[86:89]
	v_mfma_f32_16x16x32_bf16 v[82:85], v[170:173], v[194:197], v[82:85]
	v_mfma_f32_16x16x32_bf16 v[70:73], v[162:165], v[208:211], v[70:73]
	v_mfma_f32_16x16x32_bf16 v[66:69], v[170:173], v[208:211], v[66:69]
	v_mfma_f32_16x16x32_bf16 v[118:121], v[166:169], v[182:185], v[118:121]
	v_mfma_f32_16x16x32_bf16 v[114:117], v[174:177], v[182:185], v[114:117]
	v_mfma_f32_16x16x32_bf16 v[102:105], v[166:169], v[190:193], v[102:105]
	v_mfma_f32_16x16x32_bf16 v[98:101], v[174:177], v[190:193], v[98:101]
	v_mfma_f32_16x16x32_bf16 v[86:89], v[166:169], v[198:201], v[86:89]
	v_mfma_f32_16x16x32_bf16 v[82:85], v[174:177], v[198:201], v[82:85]
	v_mfma_f32_16x16x32_bf16 v[70:73], v[166:169], v[212:215], v[70:73]
	v_mfma_f32_16x16x32_bf16 v[66:69], v[174:177], v[212:215], v[66:69]
	s_barrier
	s_setprio 0
	s_add_i32 s0, s33, s34
	s_mov_b32 m0, s0
	ds_read_b128 v[178:181], v153 offset:16384
	ds_read_b128 v[182:185], v153 offset:17408
	ds_read_b128 v[186:189], v153 offset:18432
	ds_read_b128 v[190:193], v153 offset:19456
	ds_read_b128 v[194:197], v153 offset:20480
	ds_read_b128 v[198:201], v153 offset:21504
	ds_read_b128 v[208:211], v153 offset:22528
	ds_read_b128 v[212:215], v153 offset:23552
	global_load_lds_dwordx4 v132, s[26:27]
	s_add_i32 m0, s0, 0x2000
	s_add_u32 s0, s26, 0x80000
	s_addc_u32 s1, s27, 0
	s_add_i32 s33, s55, s34
	global_load_lds_dwordx4 v136, s[26:27]
	s_mov_b32 m0, s33
	s_nop 0
	global_load_lds_dwordx4 v132, s[0:1]
	s_add_i32 m0, s33, 0x2000
	s_nop 0
	global_load_lds_dwordx4 v136, s[0:1]
	s_mov_b32 m0, s9
	s_nop 0
	global_load_lds_dwordx4 v130, s[28:29]
	s_mov_b32 m0, s35
	s_nop 0
	global_load_lds_dwordx4 v134, s[28:29]
	s_waitcnt vmcnt(8)
	s_waitcnt lgkmcnt(0)
	s_setprio 1
	s_barrier
	v_mfma_f32_16x16x32_bf16 v[62:65], v[142:145], v[178:181], v[62:65]
	v_mfma_f32_16x16x32_bf16 v[58:61], v[154:157], v[178:181], v[58:61]
	v_mfma_f32_16x16x32_bf16 v[46:49], v[142:145], v[186:189], v[46:49]
	v_mfma_f32_16x16x32_bf16 v[42:45], v[154:157], v[186:189], v[42:45]
	v_mfma_f32_16x16x32_bf16 v[30:33], v[142:145], v[194:197], v[30:33]
	v_mfma_f32_16x16x32_bf16 v[26:29], v[154:157], v[194:197], v[26:29]
	v_mfma_f32_16x16x32_bf16 v[14:17], v[142:145], v[208:211], v[14:17]
	v_mfma_f32_16x16x32_bf16 v[10:13], v[154:157], v[208:211], v[10:13]
	v_mfma_f32_16x16x32_bf16 v[62:65], v[146:149], v[182:185], v[62:65]
	v_mfma_f32_16x16x32_bf16 v[58:61], v[158:161], v[182:185], v[58:61]
	v_mfma_f32_16x16x32_bf16 v[46:49], v[146:149], v[190:193], v[46:49]
	v_mfma_f32_16x16x32_bf16 v[42:45], v[158:161], v[190:193], v[42:45]
	v_mfma_f32_16x16x32_bf16 v[30:33], v[146:149], v[198:201], v[30:33]
	v_mfma_f32_16x16x32_bf16 v[26:29], v[158:161], v[198:201], v[26:29]
	v_mfma_f32_16x16x32_bf16 v[14:17], v[146:149], v[212:215], v[14:17]
	v_mfma_f32_16x16x32_bf16 v[10:13], v[158:161], v[212:215], v[10:13]
	v_mfma_f32_16x16x32_bf16 v[54:57], v[162:165], v[178:181], v[54:57]
	v_mfma_f32_16x16x32_bf16 v[50:53], v[170:173], v[178:181], v[50:53]
	v_mfma_f32_16x16x32_bf16 v[38:41], v[162:165], v[186:189], v[38:41]
	v_mfma_f32_16x16x32_bf16 v[34:37], v[170:173], v[186:189], v[34:37]
	v_mfma_f32_16x16x32_bf16 v[22:25], v[162:165], v[194:197], v[22:25]
	v_mfma_f32_16x16x32_bf16 v[18:21], v[170:173], v[194:197], v[18:21]
	v_mfma_f32_16x16x32_bf16 v[6:9], v[162:165], v[208:211], v[6:9]
	v_mfma_f32_16x16x32_bf16 v[2:5], v[170:173], v[208:211], v[2:5]
	v_mfma_f32_16x16x32_bf16 v[54:57], v[166:169], v[182:185], v[54:57]
	v_mfma_f32_16x16x32_bf16 v[50:53], v[174:177], v[182:185], v[50:53]
	v_mfma_f32_16x16x32_bf16 v[38:41], v[166:169], v[190:193], v[38:41]
	v_mfma_f32_16x16x32_bf16 v[34:37], v[174:177], v[190:193], v[34:37]
	v_mfma_f32_16x16x32_bf16 v[22:25], v[166:169], v[198:201], v[22:25]
	v_mfma_f32_16x16x32_bf16 v[18:21], v[174:177], v[198:201], v[18:21]
	v_mfma_f32_16x16x32_bf16 v[6:9], v[166:169], v[212:215], v[6:9]
	v_mfma_f32_16x16x32_bf16 v[2:5], v[174:177], v[212:215], v[2:5]
	s_barrier
	s_setprio 0
	s_add_i32 s33, 0, 0x18000
	s_add_i32 s55, 0, 0x1c000
	ds_read_b128 v[142:145], v151 offset:32768
	ds_read_b128 v[146:149], v151 offset:33792
	ds_read_b128 v[154:157], v151 offset:34816
	ds_read_b128 v[158:161], v151 offset:35840
	ds_read_b128 v[162:165], v151 offset:49152
	ds_read_b128 v[166:169], v151 offset:50176
	ds_read_b128 v[170:173], v151 offset:51200
	ds_read_b128 v[174:177], v151 offset:52224
	s_add_u32 s0, s28, 0x80000
	s_addc_u32 s1, s29, 0
	s_mov_b32 m0, s36
	ds_read_b128 v[178:181], v153 offset:32768
	ds_read_b128 v[182:185], v153 offset:33792
	ds_read_b128 v[186:189], v153 offset:34816
	ds_read_b128 v[190:193], v153 offset:35840
	ds_read_b128 v[194:197], v153 offset:36864
	ds_read_b128 v[198:201], v153 offset:37888
	ds_read_b128 v[208:211], v153 offset:38912
	ds_read_b128 v[212:215], v153 offset:39936
	global_load_lds_dwordx4 v130, s[0:1]
	s_mov_b32 m0, s37
	s_nop 0
	global_load_lds_dwordx4 v134, s[0:1]
	s_waitcnt vmcnt(8)
	s_waitcnt lgkmcnt(0)
	s_setprio 1
	s_barrier
	v_mfma_f32_16x16x32_bf16 v[126:129], v[142:145], v[178:181], v[126:129]
	v_mfma_f32_16x16x32_bf16 v[122:125], v[154:157], v[178:181], v[122:125]
	v_mfma_f32_16x16x32_bf16 v[110:113], v[142:145], v[186:189], v[110:113]
	v_mfma_f32_16x16x32_bf16 v[106:109], v[154:157], v[186:189], v[106:109]
	v_mfma_f32_16x16x32_bf16 v[94:97], v[142:145], v[194:197], v[94:97]
	v_mfma_f32_16x16x32_bf16 v[90:93], v[154:157], v[194:197], v[90:93]
	v_mfma_f32_16x16x32_bf16 v[78:81], v[142:145], v[208:211], v[78:81]
	v_mfma_f32_16x16x32_bf16 v[74:77], v[154:157], v[208:211], v[74:77]
	v_mfma_f32_16x16x32_bf16 v[126:129], v[146:149], v[182:185], v[126:129]
	v_mfma_f32_16x16x32_bf16 v[122:125], v[158:161], v[182:185], v[122:125]
	v_mfma_f32_16x16x32_bf16 v[110:113], v[146:149], v[190:193], v[110:113]
	v_mfma_f32_16x16x32_bf16 v[106:109], v[158:161], v[190:193], v[106:109]
	v_mfma_f32_16x16x32_bf16 v[94:97], v[146:149], v[198:201], v[94:97]
	v_mfma_f32_16x16x32_bf16 v[90:93], v[158:161], v[198:201], v[90:93]
	v_mfma_f32_16x16x32_bf16 v[78:81], v[146:149], v[212:215], v[78:81]
	v_mfma_f32_16x16x32_bf16 v[74:77], v[158:161], v[212:215], v[74:77]
	v_mfma_f32_16x16x32_bf16 v[118:121], v[162:165], v[178:181], v[118:121]
	v_mfma_f32_16x16x32_bf16 v[114:117], v[170:173], v[178:181], v[114:117]
	v_mfma_f32_16x16x32_bf16 v[102:105], v[162:165], v[186:189], v[102:105]
	v_mfma_f32_16x16x32_bf16 v[98:101], v[170:173], v[186:189], v[98:101]
	v_mfma_f32_16x16x32_bf16 v[86:89], v[162:165], v[194:197], v[86:89]
	v_mfma_f32_16x16x32_bf16 v[82:85], v[170:173], v[194:197], v[82:85]
	v_mfma_f32_16x16x32_bf16 v[70:73], v[162:165], v[208:211], v[70:73]
	v_mfma_f32_16x16x32_bf16 v[66:69], v[170:173], v[208:211], v[66:69]
	v_mfma_f32_16x16x32_bf16 v[118:121], v[166:169], v[182:185], v[118:121]
	v_mfma_f32_16x16x32_bf16 v[114:117], v[174:177], v[182:185], v[114:117]
	v_mfma_f32_16x16x32_bf16 v[102:105], v[166:169], v[190:193], v[102:105]
	v_mfma_f32_16x16x32_bf16 v[98:101], v[174:177], v[190:193], v[98:101]
	v_mfma_f32_16x16x32_bf16 v[86:89], v[166:169], v[198:201], v[86:89]
	v_mfma_f32_16x16x32_bf16 v[82:85], v[174:177], v[198:201], v[82:85]
	v_mfma_f32_16x16x32_bf16 v[70:73], v[166:169], v[212:215], v[70:73]
	v_mfma_f32_16x16x32_bf16 v[66:69], v[174:177], v[212:215], v[66:69]
	s_barrier
	s_setprio 0
.Lpeel_mid_0:
	s_add_i32 s0, s33, s34
	s_add_u32 s100, s26, 0x80
	s_addc_u32 s101, s27, 0
	s_mov_b32 m0, s0
	ds_read_b128 v[178:181], v153 offset:49152
	ds_read_b128 v[182:185], v153 offset:50176
	ds_read_b128 v[186:189], v153 offset:51200
	ds_read_b128 v[190:193], v153 offset:52224
	ds_read_b128 v[194:197], v153 offset:53248
	ds_read_b128 v[198:201], v153 offset:54272
	ds_read_b128 v[208:211], v153 offset:55296
	ds_read_b128 v[212:215], v153 offset:56320
	global_load_lds_dwordx4 v132, s[100:101]
	s_add_i32 m0, s0, 0x2000
	s_add_u32 s100, s26, 0x80
	s_addc_u32 s101, s27, 0
	s_add_u32 s0, s26, 0x80080
	s_addc_u32 s1, s27, 0
	s_add_i32 s26, s55, s34
	global_load_lds_dwordx4 v136, s[100:101]
	s_mov_b32 m0, s26
	s_nop 0
	global_load_lds_dwordx4 v132, s[0:1]
	s_add_i32 m0, s26, 0x2000
	s_nop 0
	global_load_lds_dwordx4 v136, s[0:1]
	s_add_u32 s100, s28, 0x80
	s_addc_u32 s101, s29, 0
	s_mov_b32 m0, s39
	s_nop 0
	global_load_lds_dwordx4 v130, s[100:101]
	s_add_u32 s100, s28, 0x80
	s_addc_u32 s101, s29, 0
	s_mov_b32 m0, s40
	s_nop 0
	global_load_lds_dwordx4 v134, s[100:101]
	s_waitcnt vmcnt(8)
	s_waitcnt lgkmcnt(0)
	s_setprio 1
	s_barrier
	v_mfma_f32_16x16x32_bf16 v[62:65], v[142:145], v[178:181], v[62:65]
	v_mfma_f32_16x16x32_bf16 v[58:61], v[154:157], v[178:181], v[58:61]
	v_mfma_f32_16x16x32_bf16 v[46:49], v[142:145], v[186:189], v[46:49]
	v_mfma_f32_16x16x32_bf16 v[42:45], v[154:157], v[186:189], v[42:45]
	v_mfma_f32_16x16x32_bf16 v[30:33], v[142:145], v[194:197], v[30:33]
	v_mfma_f32_16x16x32_bf16 v[26:29], v[154:157], v[194:197], v[26:29]
	v_mfma_f32_16x16x32_bf16 v[14:17], v[142:145], v[208:211], v[14:17]
	v_mfma_f32_16x16x32_bf16 v[10:13], v[154:157], v[208:211], v[10:13]
	v_mfma_f32_16x16x32_bf16 v[62:65], v[146:149], v[182:185], v[62:65]
	v_mfma_f32_16x16x32_bf16 v[58:61], v[158:161], v[182:185], v[58:61]
	v_mfma_f32_16x16x32_bf16 v[46:49], v[146:149], v[190:193], v[46:49]
	v_mfma_f32_16x16x32_bf16 v[42:45], v[158:161], v[190:193], v[42:45]
	v_mfma_f32_16x16x32_bf16 v[30:33], v[146:149], v[198:201], v[30:33]
	v_mfma_f32_16x16x32_bf16 v[26:29], v[158:161], v[198:201], v[26:29]
	v_mfma_f32_16x16x32_bf16 v[14:17], v[146:149], v[212:215], v[14:17]
	v_mfma_f32_16x16x32_bf16 v[10:13], v[158:161], v[212:215], v[10:13]
	v_mfma_f32_16x16x32_bf16 v[54:57], v[162:165], v[178:181], v[54:57]
	v_mfma_f32_16x16x32_bf16 v[50:53], v[170:173], v[178:181], v[50:53]
	v_mfma_f32_16x16x32_bf16 v[38:41], v[162:165], v[186:189], v[38:41]
	v_mfma_f32_16x16x32_bf16 v[34:37], v[170:173], v[186:189], v[34:37]
	v_mfma_f32_16x16x32_bf16 v[22:25], v[162:165], v[194:197], v[22:25]
	v_mfma_f32_16x16x32_bf16 v[18:21], v[170:173], v[194:197], v[18:21]
	v_mfma_f32_16x16x32_bf16 v[6:9], v[162:165], v[208:211], v[6:9]
	v_mfma_f32_16x16x32_bf16 v[2:5], v[170:173], v[208:211], v[2:5]
	v_mfma_f32_16x16x32_bf16 v[54:57], v[166:169], v[182:185], v[54:57]
	v_mfma_f32_16x16x32_bf16 v[50:53], v[174:177], v[182:185], v[50:53]
	v_mfma_f32_16x16x32_bf16 v[38:41], v[166:169], v[190:193], v[38:41]
	v_mfma_f32_16x16x32_bf16 v[34:37], v[174:177], v[190:193], v[34:37]
	v_mfma_f32_16x16x32_bf16 v[22:25], v[166:169], v[198:201], v[22:25]
	v_mfma_f32_16x16x32_bf16 v[18:21], v[174:177], v[198:201], v[18:21]
	v_mfma_f32_16x16x32_bf16 v[6:9], v[166:169], v[212:215], v[6:9]
	v_mfma_f32_16x16x32_bf16 v[2:5], v[174:177], v[212:215], v[2:5]
	s_barrier
	s_setprio 0
	s_add_i32 s60, s60, 2
	s_add_u32 s24, s24, 0x100
	s_addc_u32 s25, s25, 0
	s_add_u32 s58, s58, 0x100
	s_addc_u32 s59, s59, 0
	s_cmp_gt_u32 s60, 29
	s_cbranch_scc0 .LBB0_394
	s_and_b64 vcc, exec, s[14:15]
	s_cbranch_vccz .LBB0_397
	s_barrier
.LBB0_397:
	s_add_u32 s100, s19, 0x80080
	s_addc_u32 s101, s7, 0
	s_add_i32 m0, s9, 0xc000
	s_nop 0
	global_load_lds_dwordx4 v138, s[100:101]
	s_add_i32 m0, s9, 0xe000
	s_nop 0
	global_load_lds_dwordx4 v140, s[100:101]
	s_mov_b32 s101, 0x80000001
	v_med3_f32 v142, v126, s51, v236
	v_med3_f32 v143, v127, s51, v236
	v_pk_mul_f32 v[142:143], v[142:143], s[74:75] op_sel_hi:[1,0]
	v_mov_b64_e32 v[148:149], s[46:47]
	v_pk_mul_f32 v[144:145], v[142:143], v[142:143]
	s_cmp_gt_i32 s8, 15
	v_pk_fma_f32 v[146:147], v[144:145], s[76:77], v[148:149] op_sel_hi:[1,0,0] neg_lo:[1,0,0] neg_hi:[1,0,0]
	s_cselect_b64 s[24:25], -1, 0
	v_pk_fma_f32 v[146:147], v[144:145], v[146:147], s[48:49] op_sel_hi:[1,1,0]
	s_cmp_lt_i32 s8, 16
	v_pk_fma_f32 v[146:147], v[144:145], v[146:147], s[50:51] op_sel_hi:[1,1,0]
	s_nop 0
	v_pk_fma_f32 v[146:147], v[144:145], v[146:147], s[92:93] op_sel_hi:[1,1,0]
	s_nop 0
	v_pk_fma_f32 v[146:147], v[144:145], v[146:147], s[82:83] op_sel_hi:[1,1,0]
	s_nop 0
	v_pk_fma_f32 v[146:147], v[144:145], v[146:147], s[52:53] op_sel_hi:[1,1,0]
	s_nop 0
	v_pk_fma_f32 v[144:145], v[144:145], v[146:147], s[54:55] op_sel_hi:[1,1,0]
	s_nop 0
	v_pk_fma_f32 v[142:143], v[142:143], v[144:145], 0.5 op_sel_hi:[1,1,0]
	s_nop 0
	v_pk_mul_f32 v[142:143], v[126:127], v[142:143]
	v_med3_f32 v126, v128, s51, v236
	v_med3_f32 v127, v129, s51, v236
	v_pk_mul_f32 v[126:127], v[126:127], s[74:75] op_sel_hi:[1,0]
	s_nop 0
	v_pk_mul_f32 v[144:145], v[126:127], v[126:127]
	s_nop 0
	v_pk_fma_f32 v[146:147], v[144:145], s[76:77], v[148:149] op_sel_hi:[1,0,0] neg_lo:[1,0,0] neg_hi:[1,0,0]
	s_nop 0
	v_pk_fma_f32 v[146:147], v[144:145], v[146:147], s[48:49] op_sel_hi:[1,1,0]
	s_nop 0
	v_pk_fma_f32 v[146:147], v[144:145], v[146:147], s[50:51] op_sel_hi:[1,1,0]
	s_nop 0
	v_pk_fma_f32 v[146:147], v[144:145], v[146:147], s[92:93] op_sel_hi:[1,1,0]
	s_nop 0
	v_pk_fma_f32 v[146:147], v[144:145], v[146:147], s[82:83] op_sel_hi:[1,1,0]
	s_nop 0
	v_pk_fma_f32 v[146:147], v[144:145], v[146:147], s[52:53] op_sel_hi:[1,1,0]
	s_nop 0
	v_pk_fma_f32 v[144:145], v[144:145], v[146:147], s[54:55] op_sel_hi:[1,1,0]
	s_nop 0
	v_pk_fma_f32 v[126:127], v[126:127], v[144:145], 0.5 op_sel_hi:[1,1,0]
	s_nop 0
	v_pk_mul_f32 v[144:145], v[128:129], v[126:127]
	v_med3_f32 v126, v122, s51, v236
	v_med3_f32 v127, v123, s51, v236
	v_pk_mul_f32 v[126:127], v[126:127], s[74:75] op_sel_hi:[1,0]
	s_nop 0
	v_pk_mul_f32 v[128:129], v[126:127], v[126:127]
	s_nop 0
	v_pk_fma_f32 v[146:147], v[128:129], s[76:77], v[148:149] op_sel_hi:[1,0,0] neg_lo:[1,0,0] neg_hi:[1,0,0]
	s_nop 0
	v_pk_fma_f32 v[146:147], v[128:129], v[146:147], s[48:49] op_sel_hi:[1,1,0]
	s_nop 0
	v_pk_fma_f32 v[146:147], v[128:129], v[146:147], s[50:51] op_sel_hi:[1,1,0]
	s_nop 0
	v_pk_fma_f32 v[146:147], v[128:129], v[146:147], s[92:93] op_sel_hi:[1,1,0]
	s_nop 0
	v_pk_fma_f32 v[146:147], v[128:129], v[146:147], s[82:83] op_sel_hi:[1,1,0]
	s_nop 0
	v_pk_fma_f32 v[146:147], v[128:129], v[146:147], s[52:53] op_sel_hi:[1,1,0]
	s_nop 0
	v_pk_fma_f32 v[128:129], v[128:129], v[146:147], s[54:55] op_sel_hi:[1,1,0]
	s_nop 0
	v_pk_fma_f32 v[126:127], v[126:127], v[128:129], 0.5 op_sel_hi:[1,1,0]
	s_nop 0
	v_pk_mul_f32 v[146:147], v[122:123], v[126:127]
	v_med3_f32 v122, v124, s51, v236
	v_med3_f32 v123, v125, s51, v236
	v_pk_mul_f32 v[122:123], v[122:123], s[74:75] op_sel_hi:[1,0]
	s_nop 0
	v_pk_mul_f32 v[126:127], v[122:123], v[122:123]
	s_nop 0
	v_pk_fma_f32 v[128:129], v[126:127], s[76:77], v[148:149] op_sel_hi:[1,0,0] neg_lo:[1,0,0] neg_hi:[1,0,0]
	s_nop 0
	v_pk_fma_f32 v[128:129], v[126:127], v[128:129], s[48:49] op_sel_hi:[1,1,0]
	s_nop 0
	v_pk_fma_f32 v[128:129], v[126:127], v[128:129], s[50:51] op_sel_hi:[1,1,0]
	s_nop 0
	v_pk_fma_f32 v[128:129], v[126:127], v[128:129], s[92:93] op_sel_hi:[1,1,0]
	s_nop 0
	v_pk_fma_f32 v[128:129], v[126:127], v[128:129], s[82:83] op_sel_hi:[1,1,0]
	s_nop 0
	v_pk_fma_f32 v[128:129], v[126:127], v[128:129], s[52:53] op_sel_hi:[1,1,0]
	s_nop 0
	v_pk_fma_f32 v[126:127], v[126:127], v[128:129], s[54:55] op_sel_hi:[1,1,0]
	s_nop 0
	v_pk_fma_f32 v[122:123], v[122:123], v[126:127], 0.5 op_sel_hi:[1,1,0]
	s_nop 0
	v_pk_mul_f32 v[148:149], v[124:125], v[122:123]
	s_cbranch_scc1 .LBB0_399
	v_pk_mul_f32 v[124:125], v[146:147], v[146:147]
	v_pk_add_f32 v[126:127], v[144:145], v[148:149]
	v_pk_fma_f32 v[124:125], v[142:143], v[142:143], v[124:125]
	v_pk_mul_f32 v[128:129], v[144:145], v[144:145]
	v_pk_add_f32 v[124:125], v[124:125], v[124:125] op_sel_hi:[0,1]
	v_pk_add_f32 v[122:123], v[142:143], v[146:147]
	v_mov_b32_e32 v127, v129
	v_mov_b32_e32 v128, v144
	v_mov_b32_e32 v129, v148
	v_mul_f32_e32 v124, v144, v144
	v_add_f32_e32 v122, 0, v122
	v_pk_fma_f32 v[128:129], v[128:129], v[128:129], v[124:125] op_sel_hi:[1,1,0]
	v_pk_mul_f32 v[154:155], v[148:149], v[148:149]
	v_add_f32_e32 v122, v123, v122
	v_mov_b32_e32 v128, v145
	v_mov_b32_e32 v124, v149
	v_mov_b32_e32 v123, v155
	v_pk_add_f32 v[124:125], v[128:129], v[124:125]
	v_pk_add_f32 v[122:123], v[126:127], v[122:123]
	s_nop 0
	v_pk_add_f32 v[126:127], v[122:123], v[124:125]
	s_branch .LBB0_400

.LBB0_836:
	s_ashr_i32 s11, s10, 31
	s_lshl_b64 s[0:1], s[10:11], 20
	s_add_u32 s14, s42, s0
	s_addc_u32 s15, s43, s1
	s_and_b64 s[0:1], s[2:3], exec
	s_cselect_b32 s11, s15, s19
	s_cselect_b32 s38, s14, s18
	s_ashr_i32 s9, s8, 31
	s_lshl_b64 s[0:1], s[8:9], 20
	s_add_u32 s16, s24, s0
	s_addc_u32 s17, s25, s1
	s_and_b64 s[0:1], s[2:3], exec
	s_cselect_b32 s9, s17, s21
	s_cselect_b32 s39, s16, s20
	s_add_u32 s18, s18, 0x80080
	s_addc_u32 s19, s19, 0
	s_add_u32 s49, s20, 0x100
	v_mov_b32_e32 v2, 0
	s_addc_u32 s58, s21, 0
	s_mov_b32 s59, -2
	v_mov_b32_e32 v3, v2
	v_pk_mov_b32 v[4:5], v[2:3], v[2:3] op_sel:[0,1]
	v_pk_mov_b32 v[10:11], v[2:3], v[2:3] op_sel:[0,1]
	v_pk_mov_b32 v[12:13], v[2:3], v[2:3] op_sel:[0,1]
	v_pk_mov_b32 v[18:19], v[2:3], v[2:3] op_sel:[0,1]
	v_pk_mov_b32 v[20:21], v[2:3], v[2:3] op_sel:[0,1]
	v_pk_mov_b32 v[26:27], v[2:3], v[2:3] op_sel:[0,1]
	v_pk_mov_b32 v[28:29], v[2:3], v[2:3] op_sel:[0,1]
	v_pk_mov_b32 v[34:35], v[2:3], v[2:3] op_sel:[0,1]
	v_pk_mov_b32 v[36:37], v[2:3], v[2:3] op_sel:[0,1]
	v_pk_mov_b32 v[42:43], v[2:3], v[2:3] op_sel:[0,1]
	v_pk_mov_b32 v[44:45], v[2:3], v[2:3] op_sel:[0,1]
	v_pk_mov_b32 v[50:51], v[2:3], v[2:3] op_sel:[0,1]
	v_pk_mov_b32 v[52:53], v[2:3], v[2:3] op_sel:[0,1]
	v_pk_mov_b32 v[58:59], v[2:3], v[2:3] op_sel:[0,1]
	v_pk_mov_b32 v[60:61], v[2:3], v[2:3] op_sel:[0,1]
	v_pk_mov_b32 v[6:7], v[2:3], v[2:3] op_sel:[0,1]
	v_pk_mov_b32 v[8:9], v[2:3], v[2:3] op_sel:[0,1]
	v_pk_mov_b32 v[14:15], v[2:3], v[2:3] op_sel:[0,1]
	v_pk_mov_b32 v[16:17], v[2:3], v[2:3] op_sel:[0,1]
	v_pk_mov_b32 v[22:23], v[2:3], v[2:3] op_sel:[0,1]
	v_pk_mov_b32 v[24:25], v[2:3], v[2:3] op_sel:[0,1]
	v_pk_mov_b32 v[30:31], v[2:3], v[2:3] op_sel:[0,1]
	v_pk_mov_b32 v[32:33], v[2:3], v[2:3] op_sel:[0,1]
	v_pk_mov_b32 v[38:39], v[2:3], v[2:3] op_sel:[0,1]
	v_pk_mov_b32 v[40:41], v[2:3], v[2:3] op_sel:[0,1]
	v_pk_mov_b32 v[46:47], v[2:3], v[2:3] op_sel:[0,1]
	v_pk_mov_b32 v[48:49], v[2:3], v[2:3] op_sel:[0,1]
	v_pk_mov_b32 v[54:55], v[2:3], v[2:3] op_sel:[0,1]
	v_pk_mov_b32 v[56:57], v[2:3], v[2:3] op_sel:[0,1]
	v_pk_mov_b32 v[62:63], v[2:3], v[2:3] op_sel:[0,1]
	v_pk_mov_b32 v[64:65], v[2:3], v[2:3] op_sel:[0,1]
	v_pk_mov_b32 v[66:67], v[2:3], v[2:3] op_sel:[0,1]
	v_pk_mov_b32 v[68:69], v[2:3], v[2:3] op_sel:[0,1]
	v_pk_mov_b32 v[74:75], v[2:3], v[2:3] op_sel:[0,1]
	v_pk_mov_b32 v[76:77], v[2:3], v[2:3] op_sel:[0,1]
	v_pk_mov_b32 v[82:83], v[2:3], v[2:3] op_sel:[0,1]
	v_pk_mov_b32 v[84:85], v[2:3], v[2:3] op_sel:[0,1]
	v_pk_mov_b32 v[90:91], v[2:3], v[2:3] op_sel:[0,1]
	v_pk_mov_b32 v[92:93], v[2:3], v[2:3] op_sel:[0,1]
	v_pk_mov_b32 v[98:99], v[2:3], v[2:3] op_sel:[0,1]
	v_pk_mov_b32 v[100:101], v[2:3], v[2:3] op_sel:[0,1]
	v_pk_mov_b32 v[106:107], v[2:3], v[2:3] op_sel:[0,1]
	v_pk_mov_b32 v[108:109], v[2:3], v[2:3] op_sel:[0,1]
	v_pk_mov_b32 v[114:115], v[2:3], v[2:3] op_sel:[0,1]
	v_pk_mov_b32 v[116:117], v[2:3], v[2:3] op_sel:[0,1]
	v_pk_mov_b32 v[122:123], v[2:3], v[2:3] op_sel:[0,1]
	v_pk_mov_b32 v[124:125], v[2:3], v[2:3] op_sel:[0,1]
	v_pk_mov_b32 v[70:71], v[2:3], v[2:3] op_sel:[0,1]
	v_pk_mov_b32 v[72:73], v[2:3], v[2:3] op_sel:[0,1]
	v_pk_mov_b32 v[78:79], v[2:3], v[2:3] op_sel:[0,1]
	v_pk_mov_b32 v[80:81], v[2:3], v[2:3] op_sel:[0,1]
	v_pk_mov_b32 v[86:87], v[2:3], v[2:3] op_sel:[0,1]
	v_pk_mov_b32 v[88:89], v[2:3], v[2:3] op_sel:[0,1]
	v_pk_mov_b32 v[94:95], v[2:3], v[2:3] op_sel:[0,1]
	v_pk_mov_b32 v[96:97], v[2:3], v[2:3] op_sel:[0,1]
	v_pk_mov_b32 v[102:103], v[2:3], v[2:3] op_sel:[0,1]
	v_pk_mov_b32 v[104:105], v[2:3], v[2:3] op_sel:[0,1]
	v_pk_mov_b32 v[110:111], v[2:3], v[2:3] op_sel:[0,1]
	v_pk_mov_b32 v[112:113], v[2:3], v[2:3] op_sel:[0,1]
	v_pk_mov_b32 v[118:119], v[2:3], v[2:3] op_sel:[0,1]
	v_pk_mov_b32 v[120:121], v[2:3], v[2:3] op_sel:[0,1]
	v_pk_mov_b32 v[126:127], v[2:3], v[2:3] op_sel:[0,1]
	v_pk_mov_b32 v[128:129], v[2:3], v[2:3] op_sel:[0,1]
	s_cmp_eq_u32 s101, 0x80000001
	s_cbranch_scc0 .LBB0_837
	s_add_u32 s0, s18, 0xfff80080
	s_addc_u32 s1, s19, -1
	s_add_i32 s33, 0, 0x10000
	s_cmp_eq_u32 s59, 28
	s_cselect_b32 s23, s11, s1
	s_cselect_b32 s22, s38, s0
	s_cselect_b32 s21, s9, s58
	s_cselect_b32 s20, s39, s49
	s_add_i32 s55, 0, 0x14000
	ds_read_b128 v[146:149], v143
	ds_read_b128 v[150:153], v143 offset:1024
	ds_read_b128 v[154:157], v143 offset:2048
	ds_read_b128 v[158:161], v143 offset:3072
	ds_read_b128 v[162:165], v143 offset:16384
	ds_read_b128 v[166:169], v143 offset:17408
	ds_read_b128 v[170:173], v143 offset:18432
	ds_read_b128 v[174:177], v143 offset:19456
	s_add_i32 m0, s27, 0xc000
	ds_read_b128 v[178:181], v145
	ds_read_b128 v[182:185], v145 offset:1024
	ds_read_b128 v[186:189], v145 offset:2048
	ds_read_b128 v[190:193], v145 offset:3072
	ds_read_b128 v[194:197], v145 offset:4096
	ds_read_b128 v[198:201], v145 offset:5120
	ds_read_b128 v[208:211], v145 offset:6144
	ds_read_b128 v[212:215], v145 offset:7168
	s_add_i32 m0, s27, 0xe000
	s_nop 0
	s_waitcnt vmcnt(16)
	s_waitcnt lgkmcnt(0)
	s_setprio 1
	s_barrier
	v_mfma_f32_16x16x32_bf16 v[126:129], v[146:149], v[178:181], v[126:129]
	v_mfma_f32_16x16x32_bf16 v[118:121], v[154:157], v[178:181], v[118:121]
	v_mfma_f32_16x16x32_bf16 v[110:113], v[146:149], v[186:189], v[110:113]
	v_mfma_f32_16x16x32_bf16 v[102:105], v[154:157], v[186:189], v[102:105]
	v_mfma_f32_16x16x32_bf16 v[94:97], v[146:149], v[194:197], v[94:97]
	v_mfma_f32_16x16x32_bf16 v[86:89], v[154:157], v[194:197], v[86:89]
	v_mfma_f32_16x16x32_bf16 v[78:81], v[146:149], v[208:211], v[78:81]
	v_mfma_f32_16x16x32_bf16 v[70:73], v[154:157], v[208:211], v[70:73]
	v_mfma_f32_16x16x32_bf16 v[126:129], v[150:153], v[182:185], v[126:129]
	v_mfma_f32_16x16x32_bf16 v[118:121], v[158:161], v[182:185], v[118:121]
	v_mfma_f32_16x16x32_bf16 v[110:113], v[150:153], v[190:193], v[110:113]
	v_mfma_f32_16x16x32_bf16 v[102:105], v[158:161], v[190:193], v[102:105]
	v_mfma_f32_16x16x32_bf16 v[94:97], v[150:153], v[198:201], v[94:97]
	v_mfma_f32_16x16x32_bf16 v[86:89], v[158:161], v[198:201], v[86:89]
	v_mfma_f32_16x16x32_bf16 v[78:81], v[150:153], v[212:215], v[78:81]
	v_mfma_f32_16x16x32_bf16 v[70:73], v[158:161], v[212:215], v[70:73]
	v_mfma_f32_16x16x32_bf16 v[122:125], v[162:165], v[178:181], v[122:125]
	v_mfma_f32_16x16x32_bf16 v[114:117], v[170:173], v[178:181], v[114:117]
	v_mfma_f32_16x16x32_bf16 v[106:109], v[162:165], v[186:189], v[106:109]
	v_mfma_f32_16x16x32_bf16 v[98:101], v[170:173], v[186:189], v[98:101]
	v_mfma_f32_16x16x32_bf16 v[90:93], v[162:165], v[194:197], v[90:93]
	v_mfma_f32_16x16x32_bf16 v[82:85], v[170:173], v[194:197], v[82:85]
	v_mfma_f32_16x16x32_bf16 v[74:77], v[162:165], v[208:211], v[74:77]
	v_mfma_f32_16x16x32_bf16 v[66:69], v[170:173], v[208:211], v[66:69]
	v_mfma_f32_16x16x32_bf16 v[122:125], v[166:169], v[182:185], v[122:125]
	v_mfma_f32_16x16x32_bf16 v[114:117], v[174:177], v[182:185], v[114:117]
	v_mfma_f32_16x16x32_bf16 v[106:109], v[166:169], v[190:193], v[106:109]
	v_mfma_f32_16x16x32_bf16 v[98:101], v[174:177], v[190:193], v[98:101]
	v_mfma_f32_16x16x32_bf16 v[90:93], v[166:169], v[198:201], v[90:93]
	v_mfma_f32_16x16x32_bf16 v[82:85], v[174:177], v[198:201], v[82:85]
	v_mfma_f32_16x16x32_bf16 v[74:77], v[166:169], v[212:215], v[74:77]
	v_mfma_f32_16x16x32_bf16 v[66:69], v[174:177], v[212:215], v[66:69]
	s_barrier
	s_setprio 0
	s_add_i32 s0, s33, s26
	s_mov_b32 m0, s0
	ds_read_b128 v[178:181], v145 offset:16384
	ds_read_b128 v[182:185], v145 offset:17408
	ds_read_b128 v[186:189], v145 offset:18432
	ds_read_b128 v[190:193], v145 offset:19456
	ds_read_b128 v[194:197], v145 offset:20480
	ds_read_b128 v[198:201], v145 offset:21504
	ds_read_b128 v[208:211], v145 offset:22528
	ds_read_b128 v[212:215], v145 offset:23552
	global_load_lds_dwordx4 v202, s[20:21]
	s_add_i32 m0, s0, 0x2000
	s_add_u32 s0, s20, 0x80000
	s_addc_u32 s1, s21, 0
	s_add_i32 s33, s55, s26
	global_load_lds_dwordx4 v130, s[20:21]
	s_mov_b32 m0, s33
	s_nop 0
	global_load_lds_dwordx4 v202, s[0:1]
	s_add_i32 m0, s33, 0x2000
	s_nop 0
	global_load_lds_dwordx4 v130, s[0:1]
	s_mov_b32 m0, s27
	s_nop 0
	global_load_lds_dwordx4 v134, s[22:23]
	s_mov_b32 m0, s28
	s_nop 0
	global_load_lds_dwordx4 v132, s[22:23]
	s_waitcnt vmcnt(16)
	s_waitcnt lgkmcnt(0)
	s_setprio 1
	s_barrier
	v_mfma_f32_16x16x32_bf16 v[62:65], v[146:149], v[178:181], v[62:65]
	v_mfma_f32_16x16x32_bf16 v[54:57], v[154:157], v[178:181], v[54:57]
	v_mfma_f32_16x16x32_bf16 v[46:49], v[146:149], v[186:189], v[46:49]
	v_mfma_f32_16x16x32_bf16 v[38:41], v[154:157], v[186:189], v[38:41]
	v_mfma_f32_16x16x32_bf16 v[30:33], v[146:149], v[194:197], v[30:33]
	v_mfma_f32_16x16x32_bf16 v[22:25], v[154:157], v[194:197], v[22:25]
	v_mfma_f32_16x16x32_bf16 v[14:17], v[146:149], v[208:211], v[14:17]
	v_mfma_f32_16x16x32_bf16 v[6:9], v[154:157], v[208:211], v[6:9]
	v_mfma_f32_16x16x32_bf16 v[62:65], v[150:153], v[182:185], v[62:65]
	v_mfma_f32_16x16x32_bf16 v[54:57], v[158:161], v[182:185], v[54:57]
	v_mfma_f32_16x16x32_bf16 v[46:49], v[150:153], v[190:193], v[46:49]
	v_mfma_f32_16x16x32_bf16 v[38:41], v[158:161], v[190:193], v[38:41]
	v_mfma_f32_16x16x32_bf16 v[30:33], v[150:153], v[198:201], v[30:33]
	v_mfma_f32_16x16x32_bf16 v[22:25], v[158:161], v[198:201], v[22:25]
	v_mfma_f32_16x16x32_bf16 v[14:17], v[150:153], v[212:215], v[14:17]
	v_mfma_f32_16x16x32_bf16 v[6:9], v[158:161], v[212:215], v[6:9]
	v_mfma_f32_16x16x32_bf16 v[58:61], v[162:165], v[178:181], v[58:61]
	v_mfma_f32_16x16x32_bf16 v[50:53], v[170:173], v[178:181], v[50:53]
	v_mfma_f32_16x16x32_bf16 v[42:45], v[162:165], v[186:189], v[42:45]
	v_mfma_f32_16x16x32_bf16 v[34:37], v[170:173], v[186:189], v[34:37]
	v_mfma_f32_16x16x32_bf16 v[26:29], v[162:165], v[194:197], v[26:29]
	v_mfma_f32_16x16x32_bf16 v[18:21], v[170:173], v[194:197], v[18:21]
	v_mfma_f32_16x16x32_bf16 v[10:13], v[162:165], v[208:211], v[10:13]
	v_mfma_f32_16x16x32_bf16 v[2:5], v[170:173], v[208:211], v[2:5]
	v_mfma_f32_16x16x32_bf16 v[58:61], v[166:169], v[182:185], v[58:61]
	v_mfma_f32_16x16x32_bf16 v[50:53], v[174:177], v[182:185], v[50:53]
	v_mfma_f32_16x16x32_bf16 v[42:45], v[166:169], v[190:193], v[42:45]
	v_mfma_f32_16x16x32_bf16 v[34:37], v[174:177], v[190:193], v[34:37]
	v_mfma_f32_16x16x32_bf16 v[26:29], v[166:169], v[198:201], v[26:29]
	v_mfma_f32_16x16x32_bf16 v[18:21], v[174:177], v[198:201], v[18:21]
	v_mfma_f32_16x16x32_bf16 v[10:13], v[166:169], v[212:215], v[10:13]
	v_mfma_f32_16x16x32_bf16 v[2:5], v[174:177], v[212:215], v[2:5]
	s_barrier
	s_setprio 0
	s_add_i32 s33, 0, 0x18000
	s_add_i32 s55, 0, 0x1c000
	ds_read_b128 v[146:149], v143 offset:32768
	ds_read_b128 v[150:153], v143 offset:33792
	ds_read_b128 v[154:157], v143 offset:34816
	ds_read_b128 v[158:161], v143 offset:35840
	ds_read_b128 v[162:165], v143 offset:49152
	ds_read_b128 v[166:169], v143 offset:50176
	ds_read_b128 v[170:173], v143 offset:51200
	ds_read_b128 v[174:177], v143 offset:52224
	s_add_u32 s0, s22, 0x80000
	s_addc_u32 s1, s23, 0
	s_mov_b32 m0, s29
	ds_read_b128 v[178:181], v145 offset:32768
	ds_read_b128 v[182:185], v145 offset:33792
	ds_read_b128 v[186:189], v145 offset:34816
	ds_read_b128 v[190:193], v145 offset:35840
	ds_read_b128 v[194:197], v145 offset:36864
	ds_read_b128 v[198:201], v145 offset:37888
	ds_read_b128 v[208:211], v145 offset:38912
	ds_read_b128 v[212:215], v145 offset:39936
	global_load_lds_dwordx4 v134, s[0:1]
	s_mov_b32 m0, s30
	s_nop 0
	global_load_lds_dwordx4 v132, s[0:1]
	s_waitcnt vmcnt(16)
	s_waitcnt lgkmcnt(0)
	s_setprio 1
	s_barrier
	v_mfma_f32_16x16x32_bf16 v[126:129], v[146:149], v[178:181], v[126:129]
	v_mfma_f32_16x16x32_bf16 v[118:121], v[154:157], v[178:181], v[118:121]
	v_mfma_f32_16x16x32_bf16 v[110:113], v[146:149], v[186:189], v[110:113]
	v_mfma_f32_16x16x32_bf16 v[102:105], v[154:157], v[186:189], v[102:105]
	v_mfma_f32_16x16x32_bf16 v[94:97], v[146:149], v[194:197], v[94:97]
	v_mfma_f32_16x16x32_bf16 v[86:89], v[154:157], v[194:197], v[86:89]
	v_mfma_f32_16x16x32_bf16 v[78:81], v[146:149], v[208:211], v[78:81]
	v_mfma_f32_16x16x32_bf16 v[70:73], v[154:157], v[208:211], v[70:73]
	v_mfma_f32_16x16x32_bf16 v[126:129], v[150:153], v[182:185], v[126:129]
	v_mfma_f32_16x16x32_bf16 v[118:121], v[158:161], v[182:185], v[118:121]
	v_mfma_f32_16x16x32_bf16 v[110:113], v[150:153], v[190:193], v[110:113]
	v_mfma_f32_16x16x32_bf16 v[102:105], v[158:161], v[190:193], v[102:105]
	v_mfma_f32_16x16x32_bf16 v[94:97], v[150:153], v[198:201], v[94:97]
	v_mfma_f32_16x16x32_bf16 v[86:89], v[158:161], v[198:201], v[86:89]
	v_mfma_f32_16x16x32_bf16 v[78:81], v[150:153], v[212:215], v[78:81]
	v_mfma_f32_16x16x32_bf16 v[70:73], v[158:161], v[212:215], v[70:73]
	v_mfma_f32_16x16x32_bf16 v[122:125], v[162:165], v[178:181], v[122:125]
	v_mfma_f32_16x16x32_bf16 v[114:117], v[170:173], v[178:181], v[114:117]
	v_mfma_f32_16x16x32_bf16 v[106:109], v[162:165], v[186:189], v[106:109]
	v_mfma_f32_16x16x32_bf16 v[98:101], v[170:173], v[186:189], v[98:101]
	v_mfma_f32_16x16x32_bf16 v[90:93], v[162:165], v[194:197], v[90:93]
	v_mfma_f32_16x16x32_bf16 v[82:85], v[170:173], v[194:197], v[82:85]
	v_mfma_f32_16x16x32_bf16 v[74:77], v[162:165], v[208:211], v[74:77]
	v_mfma_f32_16x16x32_bf16 v[66:69], v[170:173], v[208:211], v[66:69]
	v_mfma_f32_16x16x32_bf16 v[122:125], v[166:169], v[182:185], v[122:125]
	v_mfma_f32_16x16x32_bf16 v[114:117], v[174:177], v[182:185], v[114:117]
	v_mfma_f32_16x16x32_bf16 v[106:109], v[166:169], v[190:193], v[106:109]
	v_mfma_f32_16x16x32_bf16 v[98:101], v[174:177], v[190:193], v[98:101]
	v_mfma_f32_16x16x32_bf16 v[90:93], v[166:169], v[198:201], v[90:93]
	v_mfma_f32_16x16x32_bf16 v[82:85], v[174:177], v[198:201], v[82:85]
	v_mfma_f32_16x16x32_bf16 v[74:77], v[166:169], v[212:215], v[74:77]
	v_mfma_f32_16x16x32_bf16 v[66:69], v[174:177], v[212:215], v[66:69]
	s_barrier
	s_setprio 0
	s_branch .Lpeel_mid_3
.LBB0_837:
	s_add_u32 s0, s18, 0xfff80080
	s_addc_u32 s1, s19, -1
	s_add_i32 s33, 0, 0x10000
	s_cmp_eq_u32 s59, 28
	s_cselect_b32 s23, s11, s1
	s_cselect_b32 s22, s38, s0
	s_cselect_b32 s21, s9, s58
	s_cselect_b32 s20, s39, s49
	s_add_i32 s55, 0, 0x14000
	ds_read_b128 v[146:149], v143
	ds_read_b128 v[150:153], v143 offset:1024
	ds_read_b128 v[154:157], v143 offset:2048
	ds_read_b128 v[158:161], v143 offset:3072
	ds_read_b128 v[162:165], v143 offset:16384
	ds_read_b128 v[166:169], v143 offset:17408
	ds_read_b128 v[170:173], v143 offset:18432
	ds_read_b128 v[174:177], v143 offset:19456
	s_add_i32 m0, s27, 0xc000
	ds_read_b128 v[178:181], v145
	ds_read_b128 v[182:185], v145 offset:1024
	ds_read_b128 v[186:189], v145 offset:2048
	ds_read_b128 v[190:193], v145 offset:3072
	ds_read_b128 v[194:197], v145 offset:4096
	ds_read_b128 v[198:201], v145 offset:5120
	ds_read_b128 v[208:211], v145 offset:6144
	ds_read_b128 v[212:215], v145 offset:7168
	global_load_lds_dwordx4 v136, s[18:19]
	s_add_i32 m0, s27, 0xe000
	s_nop 0
	global_load_lds_dwordx4 v138, s[18:19]
	s_waitcnt vmcnt(8)
	s_waitcnt lgkmcnt(0)
	s_setprio 1
	s_barrier
	v_mfma_f32_16x16x32_bf16 v[126:129], v[146:149], v[178:181], v[126:129]
	v_mfma_f32_16x16x32_bf16 v[118:121], v[154:157], v[178:181], v[118:121]
	v_mfma_f32_16x16x32_bf16 v[110:113], v[146:149], v[186:189], v[110:113]
	v_mfma_f32_16x16x32_bf16 v[102:105], v[154:157], v[186:189], v[102:105]
	v_mfma_f32_16x16x32_bf16 v[94:97], v[146:149], v[194:197], v[94:97]
	v_mfma_f32_16x16x32_bf16 v[86:89], v[154:157], v[194:197], v[86:89]
	v_mfma_f32_16x16x32_bf16 v[78:81], v[146:149], v[208:211], v[78:81]
	v_mfma_f32_16x16x32_bf16 v[70:73], v[154:157], v[208:211], v[70:73]
	v_mfma_f32_16x16x32_bf16 v[126:129], v[150:153], v[182:185], v[126:129]
	v_mfma_f32_16x16x32_bf16 v[118:121], v[158:161], v[182:185], v[118:121]
	v_mfma_f32_16x16x32_bf16 v[110:113], v[150:153], v[190:193], v[110:113]
	v_mfma_f32_16x16x32_bf16 v[102:105], v[158:161], v[190:193], v[102:105]
	v_mfma_f32_16x16x32_bf16 v[94:97], v[150:153], v[198:201], v[94:97]
	v_mfma_f32_16x16x32_bf16 v[86:89], v[158:161], v[198:201], v[86:89]
	v_mfma_f32_16x16x32_bf16 v[78:81], v[150:153], v[212:215], v[78:81]
	v_mfma_f32_16x16x32_bf16 v[70:73], v[158:161], v[212:215], v[70:73]
	v_mfma_f32_16x16x32_bf16 v[122:125], v[162:165], v[178:181], v[122:125]
	v_mfma_f32_16x16x32_bf16 v[114:117], v[170:173], v[178:181], v[114:117]
	v_mfma_f32_16x16x32_bf16 v[106:109], v[162:165], v[186:189], v[106:109]
	v_mfma_f32_16x16x32_bf16 v[98:101], v[170:173], v[186:189], v[98:101]
	v_mfma_f32_16x16x32_bf16 v[90:93], v[162:165], v[194:197], v[90:93]
	v_mfma_f32_16x16x32_bf16 v[82:85], v[170:173], v[194:197], v[82:85]
	v_mfma_f32_16x16x32_bf16 v[74:77], v[162:165], v[208:211], v[74:77]
	v_mfma_f32_16x16x32_bf16 v[66:69], v[170:173], v[208:211], v[66:69]
	v_mfma_f32_16x16x32_bf16 v[122:125], v[166:169], v[182:185], v[122:125]
	v_mfma_f32_16x16x32_bf16 v[114:117], v[174:177], v[182:185], v[114:117]
	v_mfma_f32_16x16x32_bf16 v[106:109], v[166:169], v[190:193], v[106:109]
	v_mfma_f32_16x16x32_bf16 v[98:101], v[174:177], v[190:193], v[98:101]
	v_mfma_f32_16x16x32_bf16 v[90:93], v[166:169], v[198:201], v[90:93]
	v_mfma_f32_16x16x32_bf16 v[82:85], v[174:177], v[198:201], v[82:85]
	v_mfma_f32_16x16x32_bf16 v[74:77], v[166:169], v[212:215], v[74:77]
	v_mfma_f32_16x16x32_bf16 v[66:69], v[174:177], v[212:215], v[66:69]
	s_barrier
	s_setprio 0
	s_add_i32 s0, s33, s26
	s_mov_b32 m0, s0
	ds_read_b128 v[178:181], v145 offset:16384
	ds_read_b128 v[182:185], v145 offset:17408
	ds_read_b128 v[186:189], v145 offset:18432
	ds_read_b128 v[190:193], v145 offset:19456
	ds_read_b128 v[194:197], v145 offset:20480
	ds_read_b128 v[198:201], v145 offset:21504
	ds_read_b128 v[208:211], v145 offset:22528
	ds_read_b128 v[212:215], v145 offset:23552
	global_load_lds_dwordx4 v202, s[20:21]
	s_add_i32 m0, s0, 0x2000
	s_add_u32 s0, s20, 0x80000
	s_addc_u32 s1, s21, 0
	s_add_i32 s33, s55, s26
	global_load_lds_dwordx4 v130, s[20:21]
	s_mov_b32 m0, s33
	s_nop 0
	global_load_lds_dwordx4 v202, s[0:1]
	s_add_i32 m0, s33, 0x2000
	s_nop 0
	global_load_lds_dwordx4 v130, s[0:1]
	s_mov_b32 m0, s27
	s_nop 0
	global_load_lds_dwordx4 v134, s[22:23]
	s_mov_b32 m0, s28
	s_nop 0
	global_load_lds_dwordx4 v132, s[22:23]
	s_waitcnt vmcnt(8)
	s_waitcnt lgkmcnt(0)
	s_setprio 1
	s_barrier
	v_mfma_f32_16x16x32_bf16 v[62:65], v[146:149], v[178:181], v[62:65]
	v_mfma_f32_16x16x32_bf16 v[54:57], v[154:157], v[178:181], v[54:57]
	v_mfma_f32_16x16x32_bf16 v[46:49], v[146:149], v[186:189], v[46:49]
	v_mfma_f32_16x16x32_bf16 v[38:41], v[154:157], v[186:189], v[38:41]
	v_mfma_f32_16x16x32_bf16 v[30:33], v[146:149], v[194:197], v[30:33]
	v_mfma_f32_16x16x32_bf16 v[22:25], v[154:157], v[194:197], v[22:25]
	v_mfma_f32_16x16x32_bf16 v[14:17], v[146:149], v[208:211], v[14:17]
	v_mfma_f32_16x16x32_bf16 v[6:9], v[154:157], v[208:211], v[6:9]
	v_mfma_f32_16x16x32_bf16 v[62:65], v[150:153], v[182:185], v[62:65]
	v_mfma_f32_16x16x32_bf16 v[54:57], v[158:161], v[182:185], v[54:57]
	v_mfma_f32_16x16x32_bf16 v[46:49], v[150:153], v[190:193], v[46:49]
	v_mfma_f32_16x16x32_bf16 v[38:41], v[158:161], v[190:193], v[38:41]
	v_mfma_f32_16x16x32_bf16 v[30:33], v[150:153], v[198:201], v[30:33]
	v_mfma_f32_16x16x32_bf16 v[22:25], v[158:161], v[198:201], v[22:25]
	v_mfma_f32_16x16x32_bf16 v[14:17], v[150:153], v[212:215], v[14:17]
	v_mfma_f32_16x16x32_bf16 v[6:9], v[158:161], v[212:215], v[6:9]
	v_mfma_f32_16x16x32_bf16 v[58:61], v[162:165], v[178:181], v[58:61]
	v_mfma_f32_16x16x32_bf16 v[50:53], v[170:173], v[178:181], v[50:53]
	v_mfma_f32_16x16x32_bf16 v[42:45], v[162:165], v[186:189], v[42:45]
	v_mfma_f32_16x16x32_bf16 v[34:37], v[170:173], v[186:189], v[34:37]
	v_mfma_f32_16x16x32_bf16 v[26:29], v[162:165], v[194:197], v[26:29]
	v_mfma_f32_16x16x32_bf16 v[18:21], v[170:173], v[194:197], v[18:21]
	v_mfma_f32_16x16x32_bf16 v[10:13], v[162:165], v[208:211], v[10:13]
	v_mfma_f32_16x16x32_bf16 v[2:5], v[170:173], v[208:211], v[2:5]
	v_mfma_f32_16x16x32_bf16 v[58:61], v[166:169], v[182:185], v[58:61]
	v_mfma_f32_16x16x32_bf16 v[50:53], v[174:177], v[182:185], v[50:53]
	v_mfma_f32_16x16x32_bf16 v[42:45], v[166:169], v[190:193], v[42:45]
	v_mfma_f32_16x16x32_bf16 v[34:37], v[174:177], v[190:193], v[34:37]
	v_mfma_f32_16x16x32_bf16 v[26:29], v[166:169], v[198:201], v[26:29]
	v_mfma_f32_16x16x32_bf16 v[18:21], v[174:177], v[198:201], v[18:21]
	v_mfma_f32_16x16x32_bf16 v[10:13], v[166:169], v[212:215], v[10:13]
	v_mfma_f32_16x16x32_bf16 v[2:5], v[174:177], v[212:215], v[2:5]
	s_barrier
	s_setprio 0
	s_add_i32 s33, 0, 0x18000
	s_add_i32 s55, 0, 0x1c000
	ds_read_b128 v[146:149], v143 offset:32768
	ds_read_b128 v[150:153], v143 offset:33792
	ds_read_b128 v[154:157], v143 offset:34816
	ds_read_b128 v[158:161], v143 offset:35840
	ds_read_b128 v[162:165], v143 offset:49152
	ds_read_b128 v[166:169], v143 offset:50176
	ds_read_b128 v[170:173], v143 offset:51200
	ds_read_b128 v[174:177], v143 offset:52224
	s_add_u32 s0, s22, 0x80000
	s_addc_u32 s1, s23, 0
	s_mov_b32 m0, s29
	ds_read_b128 v[178:181], v145 offset:32768
	ds_read_b128 v[182:185], v145 offset:33792
	ds_read_b128 v[186:189], v145 offset:34816
	ds_read_b128 v[190:193], v145 offset:35840
	ds_read_b128 v[194:197], v145 offset:36864
	ds_read_b128 v[198:201], v145 offset:37888
	ds_read_b128 v[208:211], v145 offset:38912
	ds_read_b128 v[212:215], v145 offset:39936
	global_load_lds_dwordx4 v134, s[0:1]
	s_mov_b32 m0, s30
	s_nop 0
	global_load_lds_dwordx4 v132, s[0:1]
	s_waitcnt vmcnt(8)
	s_waitcnt lgkmcnt(0)
	s_setprio 1
	s_barrier
	v_mfma_f32_16x16x32_bf16 v[126:129], v[146:149], v[178:181], v[126:129]
	v_mfma_f32_16x16x32_bf16 v[118:121], v[154:157], v[178:181], v[118:121]
	v_mfma_f32_16x16x32_bf16 v[110:113], v[146:149], v[186:189], v[110:113]
	v_mfma_f32_16x16x32_bf16 v[102:105], v[154:157], v[186:189], v[102:105]
	v_mfma_f32_16x16x32_bf16 v[94:97], v[146:149], v[194:197], v[94:97]
	v_mfma_f32_16x16x32_bf16 v[86:89], v[154:157], v[194:197], v[86:89]
	v_mfma_f32_16x16x32_bf16 v[78:81], v[146:149], v[208:211], v[78:81]
	v_mfma_f32_16x16x32_bf16 v[70:73], v[154:157], v[208:211], v[70:73]
	v_mfma_f32_16x16x32_bf16 v[126:129], v[150:153], v[182:185], v[126:129]
	v_mfma_f32_16x16x32_bf16 v[118:121], v[158:161], v[182:185], v[118:121]
	v_mfma_f32_16x16x32_bf16 v[110:113], v[150:153], v[190:193], v[110:113]
	v_mfma_f32_16x16x32_bf16 v[102:105], v[158:161], v[190:193], v[102:105]
	v_mfma_f32_16x16x32_bf16 v[94:97], v[150:153], v[198:201], v[94:97]
	v_mfma_f32_16x16x32_bf16 v[86:89], v[158:161], v[198:201], v[86:89]
	v_mfma_f32_16x16x32_bf16 v[78:81], v[150:153], v[212:215], v[78:81]
	v_mfma_f32_16x16x32_bf16 v[70:73], v[158:161], v[212:215], v[70:73]
	v_mfma_f32_16x16x32_bf16 v[122:125], v[162:165], v[178:181], v[122:125]
	v_mfma_f32_16x16x32_bf16 v[114:117], v[170:173], v[178:181], v[114:117]
	v_mfma_f32_16x16x32_bf16 v[106:109], v[162:165], v[186:189], v[106:109]
	v_mfma_f32_16x16x32_bf16 v[98:101], v[170:173], v[186:189], v[98:101]
	v_mfma_f32_16x16x32_bf16 v[90:93], v[162:165], v[194:197], v[90:93]
	v_mfma_f32_16x16x32_bf16 v[82:85], v[170:173], v[194:197], v[82:85]
	v_mfma_f32_16x16x32_bf16 v[74:77], v[162:165], v[208:211], v[74:77]
	v_mfma_f32_16x16x32_bf16 v[66:69], v[170:173], v[208:211], v[66:69]
	v_mfma_f32_16x16x32_bf16 v[122:125], v[166:169], v[182:185], v[122:125]
	v_mfma_f32_16x16x32_bf16 v[114:117], v[174:177], v[182:185], v[114:117]
	v_mfma_f32_16x16x32_bf16 v[106:109], v[166:169], v[190:193], v[106:109]
	v_mfma_f32_16x16x32_bf16 v[98:101], v[174:177], v[190:193], v[98:101]
	v_mfma_f32_16x16x32_bf16 v[90:93], v[166:169], v[198:201], v[90:93]
	v_mfma_f32_16x16x32_bf16 v[82:85], v[174:177], v[198:201], v[82:85]
	v_mfma_f32_16x16x32_bf16 v[74:77], v[166:169], v[212:215], v[74:77]
	v_mfma_f32_16x16x32_bf16 v[66:69], v[174:177], v[212:215], v[66:69]
	s_barrier
	s_setprio 0
.Lpeel_mid_3:
	s_add_i32 s0, s33, s26
	s_add_u32 s100, s20, 0x80
	s_addc_u32 s101, s21, 0
	s_mov_b32 m0, s0
	ds_read_b128 v[178:181], v145 offset:49152
	ds_read_b128 v[182:185], v145 offset:50176
	ds_read_b128 v[186:189], v145 offset:51200
	ds_read_b128 v[190:193], v145 offset:52224
	ds_read_b128 v[194:197], v145 offset:53248
	ds_read_b128 v[198:201], v145 offset:54272
	ds_read_b128 v[208:211], v145 offset:55296
	ds_read_b128 v[212:215], v145 offset:56320
	global_load_lds_dwordx4 v202, s[100:101]
	s_add_i32 m0, s0, 0x2000
	s_add_u32 s100, s20, 0x80
	s_addc_u32 s101, s21, 0
	s_add_u32 s0, s20, 0x80080
	s_addc_u32 s1, s21, 0
	s_add_i32 s20, s55, s26
	global_load_lds_dwordx4 v130, s[100:101]
	s_mov_b32 m0, s20
	s_nop 0
	global_load_lds_dwordx4 v202, s[0:1]
	s_add_i32 m0, s20, 0x2000
	s_nop 0
	global_load_lds_dwordx4 v130, s[0:1]
	s_add_u32 s100, s22, 0x80
	s_addc_u32 s101, s23, 0
	s_mov_b32 m0, s31
	s_nop 0
	global_load_lds_dwordx4 v134, s[100:101]
	s_add_u32 s100, s22, 0x80
	s_addc_u32 s101, s23, 0
	s_mov_b32 m0, s34
	s_nop 0
	global_load_lds_dwordx4 v132, s[100:101]
	s_waitcnt vmcnt(8)
	s_waitcnt lgkmcnt(0)
	s_setprio 1
	s_barrier
	v_mfma_f32_16x16x32_bf16 v[62:65], v[146:149], v[178:181], v[62:65]
	v_mfma_f32_16x16x32_bf16 v[54:57], v[154:157], v[178:181], v[54:57]
	v_mfma_f32_16x16x32_bf16 v[46:49], v[146:149], v[186:189], v[46:49]
	v_mfma_f32_16x16x32_bf16 v[38:41], v[154:157], v[186:189], v[38:41]
	v_mfma_f32_16x16x32_bf16 v[30:33], v[146:149], v[194:197], v[30:33]
	v_mfma_f32_16x16x32_bf16 v[22:25], v[154:157], v[194:197], v[22:25]
	v_mfma_f32_16x16x32_bf16 v[14:17], v[146:149], v[208:211], v[14:17]
	v_mfma_f32_16x16x32_bf16 v[6:9], v[154:157], v[208:211], v[6:9]
	v_mfma_f32_16x16x32_bf16 v[62:65], v[150:153], v[182:185], v[62:65]
	v_mfma_f32_16x16x32_bf16 v[54:57], v[158:161], v[182:185], v[54:57]
	v_mfma_f32_16x16x32_bf16 v[46:49], v[150:153], v[190:193], v[46:49]
	v_mfma_f32_16x16x32_bf16 v[38:41], v[158:161], v[190:193], v[38:41]
	v_mfma_f32_16x16x32_bf16 v[30:33], v[150:153], v[198:201], v[30:33]
	v_mfma_f32_16x16x32_bf16 v[22:25], v[158:161], v[198:201], v[22:25]
	v_mfma_f32_16x16x32_bf16 v[14:17], v[150:153], v[212:215], v[14:17]
	v_mfma_f32_16x16x32_bf16 v[6:9], v[158:161], v[212:215], v[6:9]
	v_mfma_f32_16x16x32_bf16 v[58:61], v[162:165], v[178:181], v[58:61]
	v_mfma_f32_16x16x32_bf16 v[50:53], v[170:173], v[178:181], v[50:53]
	v_mfma_f32_16x16x32_bf16 v[42:45], v[162:165], v[186:189], v[42:45]
	v_mfma_f32_16x16x32_bf16 v[34:37], v[170:173], v[186:189], v[34:37]
	v_mfma_f32_16x16x32_bf16 v[26:29], v[162:165], v[194:197], v[26:29]
	v_mfma_f32_16x16x32_bf16 v[18:21], v[170:173], v[194:197], v[18:21]
	v_mfma_f32_16x16x32_bf16 v[10:13], v[162:165], v[208:211], v[10:13]
	v_mfma_f32_16x16x32_bf16 v[2:5], v[170:173], v[208:211], v[2:5]
	v_mfma_f32_16x16x32_bf16 v[58:61], v[166:169], v[182:185], v[58:61]
	v_mfma_f32_16x16x32_bf16 v[50:53], v[174:177], v[182:185], v[50:53]
	v_mfma_f32_16x16x32_bf16 v[42:45], v[166:169], v[190:193], v[42:45]
	v_mfma_f32_16x16x32_bf16 v[34:37], v[174:177], v[190:193], v[34:37]
	v_mfma_f32_16x16x32_bf16 v[26:29], v[166:169], v[198:201], v[26:29]
	v_mfma_f32_16x16x32_bf16 v[18:21], v[174:177], v[198:201], v[18:21]
	v_mfma_f32_16x16x32_bf16 v[10:13], v[166:169], v[212:215], v[10:13]
	v_mfma_f32_16x16x32_bf16 v[2:5], v[174:177], v[212:215], v[2:5]
	s_barrier
	s_setprio 0
	s_add_i32 s59, s59, 2
	s_add_u32 s18, s18, 0x100
	s_addc_u32 s19, s19, 0
	s_add_u32 s49, s49, 0x100
	s_addc_u32 s58, s58, 0
	s_cmp_gt_u32 s59, 29
	s_cbranch_scc0 .LBB0_837
	s_and_b64 vcc, exec, s[6:7]
	s_cbranch_vccz .LBB0_840
	s_barrier
.LBB0_840:
	s_add_u32 s100, s38, 0x80080
	s_addc_u32 s101, s11, 0
	s_add_i32 m0, s27, 0xc000
	s_nop 0
	global_load_lds_dwordx4 v136, s[100:101]
	s_add_i32 m0, s27, 0xe000
	s_nop 0
	global_load_lds_dwordx4 v138, s[100:101]
	s_mov_b32 s101, 0x80000001
	v_lshl_or_b32 v148, s36, 7, v144
	v_lshl_add_u32 v146, s37, 8, v142
	v_ashrrev_i32_e32 v149, 31, v148
	v_mov_b64_e32 v[140:141], s[78:79]
	v_mad_i64_i32 v[150:151], s[0:1], v146, s13, v[140:141]
	s_mov_b64 s[18:19], -1
	s_andn2_b64 vcc, exec, s[2:3]
	s_mov_b32 s100, 0xbfb8aa3b
	v_lshlrev_b64 v[184:185], 1, v[148:149]
	v_pk_mul_f32 v[152:153], v[126:127], s[100:101] op_sel_hi:[1,0]
	v_pk_mul_f32 v[154:155], v[128:129], s[100:101] op_sel_hi:[1,0]
	v_pk_mul_f32 v[156:157], v[118:119], s[100:101] op_sel_hi:[1,0]
	v_pk_mul_f32 v[158:159], v[120:121], s[100:101] op_sel_hi:[1,0]
	v_exp_f32_e32 v152, v152
	v_exp_f32_e32 v153, v153
	v_exp_f32_e32 v154, v154
	v_exp_f32_e32 v155, v155
	v_exp_f32_e32 v156, v156
	v_exp_f32_e32 v157, v157
	v_exp_f32_e32 v158, v158
	v_exp_f32_e32 v159, v159
	v_pk_add_f32 v[152:153], v[152:153], 1.0 op_sel_hi:[1,0]
	v_pk_add_f32 v[154:155], v[154:155], 1.0 op_sel_hi:[1,0]
	v_pk_add_f32 v[156:157], v[156:157], 1.0 op_sel_hi:[1,0]
	v_pk_add_f32 v[158:159], v[158:159], 1.0 op_sel_hi:[1,0]
	v_rcp_f32_e32 v152, v152
	v_rcp_f32_e32 v153, v153
	v_rcp_f32_e32 v154, v154
	v_rcp_f32_e32 v155, v155
	v_rcp_f32_e32 v156, v156
	v_rcp_f32_e32 v157, v157
	v_rcp_f32_e32 v158, v158
	v_rcp_f32_e32 v159, v159
	v_pk_mul_f32 v[126:127], v[126:127], v[152:153]
	v_pk_mul_f32 v[128:129], v[128:129], v[154:155]
	v_pk_mul_f32 v[118:119], v[118:119], v[156:157]
	v_pk_mul_f32 v[120:121], v[120:121], v[158:159]
	v_lshl_add_u64 v[164:165], v[150:151], 0, v[184:185]
	v_pk_mul_f32 v[122:123], v[126:127], v[122:123]
	v_pk_mul_f32 v[124:125], v[128:129], v[124:125]
	v_pk_mul_f32 v[114:115], v[118:119], v[114:115]
	v_pk_mul_f32 v[116:117], v[120:121], v[116:117]
	v_cvt_pk_bf16_f32 v160, v122, v123
	v_cvt_pk_bf16_f32 v161, v124, v125
	v_cvt_pk_bf16_f32 v162, v114, v115
	v_cvt_pk_bf16_f32 v163, v116, v117
	s_nop 0
	global_store_dwordx4 v[164:165], v[160:163], off
	v_pk_mul_f32 v[168:169], v[110:111], s[100:101] op_sel_hi:[1,0]
	v_pk_mul_f32 v[170:171], v[112:113], s[100:101] op_sel_hi:[1,0]
	v_pk_mul_f32 v[172:173], v[102:103], s[100:101] op_sel_hi:[1,0]
	v_pk_mul_f32 v[174:175], v[104:105], s[100:101] op_sel_hi:[1,0]
	v_exp_f32_e32 v168, v168
	v_exp_f32_e32 v169, v169
	v_exp_f32_e32 v170, v170
	v_exp_f32_e32 v171, v171
	v_exp_f32_e32 v172, v172
	v_exp_f32_e32 v173, v173
	v_exp_f32_e32 v174, v174
	v_exp_f32_e32 v175, v175
	v_pk_add_f32 v[168:169], v[168:169], 1.0 op_sel_hi:[1,0]
	v_pk_add_f32 v[170:171], v[170:171], 1.0 op_sel_hi:[1,0]
	v_pk_add_f32 v[172:173], v[172:173], 1.0 op_sel_hi:[1,0]
	v_pk_add_f32 v[174:175], v[174:175], 1.0 op_sel_hi:[1,0]
	v_rcp_f32_e32 v168, v168
	v_rcp_f32_e32 v169, v169
	v_rcp_f32_e32 v170, v170
	v_rcp_f32_e32 v171, v171
	v_rcp_f32_e32 v172, v172
	v_rcp_f32_e32 v173, v173
	v_rcp_f32_e32 v174, v174
	v_rcp_f32_e32 v175, v175
	v_pk_mul_f32 v[110:111], v[110:111], v[168:169]
	v_pk_mul_f32 v[112:113], v[112:113], v[170:171]
	v_pk_mul_f32 v[102:103], v[102:103], v[172:173]
	v_pk_mul_f32 v[104:105], v[104:105], v[174:175]
	v_or_b32_e32 v182, 16, v146
	v_pk_mul_f32 v[106:107], v[110:111], v[106:107]
	v_pk_mul_f32 v[108:109], v[112:113], v[108:109]
	v_pk_mul_f32 v[98:99], v[102:103], v[98:99]
	v_pk_mul_f32 v[100:101], v[104:105], v[100:101]
	v_mad_i64_i32 v[180:181], s[0:1], v182, s13, v[140:141]
	v_cvt_pk_bf16_f32 v176, v106, v107
	v_cvt_pk_bf16_f32 v177, v108, v109
	v_cvt_pk_bf16_f32 v178, v98, v99
	v_cvt_pk_bf16_f32 v179, v100, v101
	v_lshl_add_u64 v[180:181], v[180:181], 0, v[184:185]
	global_store_dwordx4 v[180:181], v[176:179], off
	v_pk_mul_f32 v[152:153], v[94:95], s[100:101] op_sel_hi:[1,0]
	v_pk_mul_f32 v[154:155], v[96:97], s[100:101] op_sel_hi:[1,0]
	v_pk_mul_f32 v[156:157], v[86:87], s[100:101] op_sel_hi:[1,0]
	v_pk_mul_f32 v[158:159], v[88:89], s[100:101] op_sel_hi:[1,0]
	v_exp_f32_e32 v152, v152
	v_exp_f32_e32 v153, v153
	v_exp_f32_e32 v154, v154
	v_exp_f32_e32 v155, v155
	v_exp_f32_e32 v156, v156
	v_exp_f32_e32 v157, v157
	v_exp_f32_e32 v158, v158
	v_exp_f32_e32 v159, v159
	v_pk_add_f32 v[152:153], v[152:153], 1.0 op_sel_hi:[1,0]
	v_pk_add_f32 v[154:155], v[154:155], 1.0 op_sel_hi:[1,0]
	v_pk_add_f32 v[156:157], v[156:157], 1.0 op_sel_hi:[1,0]
	v_pk_add_f32 v[158:159], v[158:159], 1.0 op_sel_hi:[1,0]
	v_rcp_f32_e32 v152, v152
	v_rcp_f32_e32 v153, v153
	v_rcp_f32_e32 v154, v154
	v_rcp_f32_e32 v155, v155
	v_rcp_f32_e32 v156, v156
	v_rcp_f32_e32 v157, v157
	v_rcp_f32_e32 v158, v158
	v_rcp_f32_e32 v159, v159
	v_pk_mul_f32 v[94:95], v[94:95], v[152:153]
	v_pk_mul_f32 v[96:97], v[96:97], v[154:155]
	v_pk_mul_f32 v[86:87], v[86:87], v[156:157]
	v_pk_mul_f32 v[88:89], v[88:89], v[158:159]
	v_or_b32_e32 v166, 32, v146
	v_pk_mul_f32 v[90:91], v[94:95], v[90:91]
	v_pk_mul_f32 v[92:93], v[96:97], v[92:93]
	v_pk_mul_f32 v[82:83], v[86:87], v[82:83]
	v_pk_mul_f32 v[84:85], v[88:89], v[84:85]
	v_mad_i64_i32 v[164:165], s[0:1], v166, s13, v[140:141]
	v_cvt_pk_bf16_f32 v160, v90, v91
	v_cvt_pk_bf16_f32 v161, v92, v93
	v_cvt_pk_bf16_f32 v162, v82, v83
	v_cvt_pk_bf16_f32 v163, v84, v85
	v_lshl_add_u64 v[164:165], v[164:165], 0, v[184:185]
	global_store_dwordx4 v[164:165], v[160:163], off
	v_pk_mul_f32 v[168:169], v[78:79], s[100:101] op_sel_hi:[1,0]
	v_pk_mul_f32 v[170:171], v[80:81], s[100:101] op_sel_hi:[1,0]
	v_pk_mul_f32 v[172:173], v[70:71], s[100:101] op_sel_hi:[1,0]
	v_pk_mul_f32 v[174:175], v[72:73], s[100:101] op_sel_hi:[1,0]
	v_exp_f32_e32 v168, v168
	v_exp_f32_e32 v169, v169
	v_exp_f32_e32 v170, v170
	v_exp_f32_e32 v171, v171
	v_exp_f32_e32 v172, v172
	v_exp_f32_e32 v173, v173
	v_exp_f32_e32 v174, v174
	v_exp_f32_e32 v175, v175
	v_pk_add_f32 v[168:169], v[168:169], 1.0 op_sel_hi:[1,0]
	v_pk_add_f32 v[170:171], v[170:171], 1.0 op_sel_hi:[1,0]
	v_pk_add_f32 v[172:173], v[172:173], 1.0 op_sel_hi:[1,0]
	v_pk_add_f32 v[174:175], v[174:175], 1.0 op_sel_hi:[1,0]
	v_rcp_f32_e32 v168, v168
	v_rcp_f32_e32 v169, v169
	v_rcp_f32_e32 v170, v170
	v_rcp_f32_e32 v171, v171
	v_rcp_f32_e32 v172, v172
	v_rcp_f32_e32 v173, v173
	v_rcp_f32_e32 v174, v174
	v_rcp_f32_e32 v175, v175
	v_pk_mul_f32 v[78:79], v[78:79], v[168:169]
	v_pk_mul_f32 v[80:81], v[80:81], v[170:171]
	v_pk_mul_f32 v[70:71], v[70:71], v[172:173]
	v_pk_mul_f32 v[72:73], v[72:73], v[174:175]
	v_or_b32_e32 v182, 48, v146
	v_pk_mul_f32 v[74:75], v[78:79], v[74:75]
	v_pk_mul_f32 v[76:77], v[80:81], v[76:77]
	v_pk_mul_f32 v[66:67], v[70:71], v[66:67]
	v_pk_mul_f32 v[68:69], v[72:73], v[68:69]
	v_mad_i64_i32 v[180:181], s[0:1], v182, s13, v[140:141]
	v_cvt_pk_bf16_f32 v176, v74, v75
	v_cvt_pk_bf16_f32 v177, v76, v77
	v_cvt_pk_bf16_f32 v178, v66, v67
	v_cvt_pk_bf16_f32 v179, v68, v69
	v_lshl_add_u64 v[180:181], v[180:181], 0, v[184:185]
	global_store_dwordx4 v[180:181], v[176:179], off
	v_pk_mul_f32 v[152:153], v[62:63], s[100:101] op_sel_hi:[1,0]
	v_pk_mul_f32 v[154:155], v[64:65], s[100:101] op_sel_hi:[1,0]
	v_pk_mul_f32 v[156:157], v[54:55], s[100:101] op_sel_hi:[1,0]
	v_pk_mul_f32 v[158:159], v[56:57], s[100:101] op_sel_hi:[1,0]
	v_exp_f32_e32 v152, v152
	v_exp_f32_e32 v153, v153
	v_exp_f32_e32 v154, v154
	v_exp_f32_e32 v155, v155
	v_exp_f32_e32 v156, v156
	v_exp_f32_e32 v157, v157
	v_exp_f32_e32 v158, v158
	v_exp_f32_e32 v159, v159
	v_pk_add_f32 v[152:153], v[152:153], 1.0 op_sel_hi:[1,0]
	v_pk_add_f32 v[154:155], v[154:155], 1.0 op_sel_hi:[1,0]
	v_pk_add_f32 v[156:157], v[156:157], 1.0 op_sel_hi:[1,0]
	v_pk_add_f32 v[158:159], v[158:159], 1.0 op_sel_hi:[1,0]
	v_rcp_f32_e32 v152, v152
	v_rcp_f32_e32 v153, v153
	v_rcp_f32_e32 v154, v154
	v_rcp_f32_e32 v155, v155
	v_rcp_f32_e32 v156, v156
	v_rcp_f32_e32 v157, v157
	v_rcp_f32_e32 v158, v158
	v_rcp_f32_e32 v159, v159
	v_pk_mul_f32 v[62:63], v[62:63], v[152:153]
	v_pk_mul_f32 v[64:65], v[64:65], v[154:155]
	v_pk_mul_f32 v[54:55], v[54:55], v[156:157]
	v_pk_mul_f32 v[56:57], v[56:57], v[158:159]
	v_add_u32_e32 v166, 0x80, v146
	v_pk_mul_f32 v[58:59], v[62:63], v[58:59]
	v_pk_mul_f32 v[60:61], v[64:65], v[60:61]
	v_pk_mul_f32 v[50:51], v[54:55], v[50:51]
	v_pk_mul_f32 v[52:53], v[56:57], v[52:53]
	v_mad_i64_i32 v[164:165], s[0:1], v166, s13, v[140:141]
	v_cvt_pk_bf16_f32 v160, v58, v59
	v_cvt_pk_bf16_f32 v161, v60, v61
	v_cvt_pk_bf16_f32 v162, v50, v51
	v_cvt_pk_bf16_f32 v163, v52, v53
	v_lshl_add_u64 v[164:165], v[164:165], 0, v[184:185]
	global_store_dwordx4 v[164:165], v[160:163], off
	v_pk_mul_f32 v[168:169], v[46:47], s[100:101] op_sel_hi:[1,0]
	v_pk_mul_f32 v[170:171], v[48:49], s[100:101] op_sel_hi:[1,0]
	v_pk_mul_f32 v[172:173], v[38:39], s[100:101] op_sel_hi:[1,0]
	v_pk_mul_f32 v[174:175], v[40:41], s[100:101] op_sel_hi:[1,0]
	v_exp_f32_e32 v168, v168
	v_exp_f32_e32 v169, v169
	v_exp_f32_e32 v170, v170
	v_exp_f32_e32 v171, v171
	v_exp_f32_e32 v172, v172
	v_exp_f32_e32 v173, v173
	v_exp_f32_e32 v174, v174
	v_exp_f32_e32 v175, v175
	v_pk_add_f32 v[168:169], v[168:169], 1.0 op_sel_hi:[1,0]
	v_pk_add_f32 v[170:171], v[170:171], 1.0 op_sel_hi:[1,0]
	v_pk_add_f32 v[172:173], v[172:173], 1.0 op_sel_hi:[1,0]
	v_pk_add_f32 v[174:175], v[174:175], 1.0 op_sel_hi:[1,0]
	v_rcp_f32_e32 v168, v168
	v_rcp_f32_e32 v169, v169
	v_rcp_f32_e32 v170, v170
	v_rcp_f32_e32 v171, v171
	v_rcp_f32_e32 v172, v172
	v_rcp_f32_e32 v173, v173
	v_rcp_f32_e32 v174, v174
	v_rcp_f32_e32 v175, v175
	v_pk_mul_f32 v[46:47], v[46:47], v[168:169]
	v_pk_mul_f32 v[48:49], v[48:49], v[170:171]
	v_pk_mul_f32 v[38:39], v[38:39], v[172:173]
	v_pk_mul_f32 v[40:41], v[40:41], v[174:175]
	v_add_u32_e32 v182, 0x90, v146
	v_pk_mul_f32 v[42:43], v[46:47], v[42:43]
	v_pk_mul_f32 v[44:45], v[48:49], v[44:45]
	v_pk_mul_f32 v[34:35], v[38:39], v[34:35]
	v_pk_mul_f32 v[36:37], v[40:41], v[36:37]
	v_mad_i64_i32 v[180:181], s[0:1], v182, s13, v[140:141]
	v_cvt_pk_bf16_f32 v176, v42, v43
	v_cvt_pk_bf16_f32 v177, v44, v45
	v_cvt_pk_bf16_f32 v178, v34, v35
	v_cvt_pk_bf16_f32 v179, v36, v37
	v_lshl_add_u64 v[180:181], v[180:181], 0, v[184:185]
	global_store_dwordx4 v[180:181], v[176:179], off
	v_pk_mul_f32 v[152:153], v[30:31], s[100:101] op_sel_hi:[1,0]
	v_pk_mul_f32 v[154:155], v[32:33], s[100:101] op_sel_hi:[1,0]
	v_pk_mul_f32 v[156:157], v[22:23], s[100:101] op_sel_hi:[1,0]
	v_pk_mul_f32 v[158:159], v[24:25], s[100:101] op_sel_hi:[1,0]
	v_exp_f32_e32 v152, v152
	v_exp_f32_e32 v153, v153
	v_exp_f32_e32 v154, v154
	v_exp_f32_e32 v155, v155
	v_exp_f32_e32 v156, v156
	v_exp_f32_e32 v157, v157
	v_exp_f32_e32 v158, v158
	v_exp_f32_e32 v159, v159
	v_pk_add_f32 v[152:153], v[152:153], 1.0 op_sel_hi:[1,0]
	v_pk_add_f32 v[154:155], v[154:155], 1.0 op_sel_hi:[1,0]
	v_pk_add_f32 v[156:157], v[156:157], 1.0 op_sel_hi:[1,0]
	v_pk_add_f32 v[158:159], v[158:159], 1.0 op_sel_hi:[1,0]
	v_rcp_f32_e32 v152, v152
	v_rcp_f32_e32 v153, v153
	v_rcp_f32_e32 v154, v154
	v_rcp_f32_e32 v155, v155
	v_rcp_f32_e32 v156, v156
	v_rcp_f32_e32 v157, v157
	v_rcp_f32_e32 v158, v158
	v_rcp_f32_e32 v159, v159
	v_pk_mul_f32 v[30:31], v[30:31], v[152:153]
	v_pk_mul_f32 v[32:33], v[32:33], v[154:155]
	v_pk_mul_f32 v[22:23], v[22:23], v[156:157]
	v_pk_mul_f32 v[24:25], v[24:25], v[158:159]
	v_add_u32_e32 v166, 0xa0, v146
	v_pk_mul_f32 v[26:27], v[30:31], v[26:27]
	v_pk_mul_f32 v[28:29], v[32:33], v[28:29]
	v_pk_mul_f32 v[18:19], v[22:23], v[18:19]
	v_pk_mul_f32 v[20:21], v[24:25], v[20:21]
	v_mad_i64_i32 v[164:165], s[0:1], v166, s13, v[140:141]
	v_cvt_pk_bf16_f32 v160, v26, v27
	v_cvt_pk_bf16_f32 v161, v28, v29
	v_cvt_pk_bf16_f32 v162, v18, v19
	v_cvt_pk_bf16_f32 v163, v20, v21
	v_lshl_add_u64 v[164:165], v[164:165], 0, v[184:185]
	global_store_dwordx4 v[164:165], v[160:163], off
	v_pk_mul_f32 v[168:169], v[14:15], s[100:101] op_sel_hi:[1,0]
	v_pk_mul_f32 v[170:171], v[16:17], s[100:101] op_sel_hi:[1,0]
	v_pk_mul_f32 v[172:173], v[6:7], s[100:101] op_sel_hi:[1,0]
	v_pk_mul_f32 v[174:175], v[8:9], s[100:101] op_sel_hi:[1,0]
	v_exp_f32_e32 v168, v168
	v_exp_f32_e32 v169, v169
	v_exp_f32_e32 v170, v170
	v_exp_f32_e32 v171, v171
	v_exp_f32_e32 v172, v172
	v_exp_f32_e32 v173, v173
	v_exp_f32_e32 v174, v174
	v_exp_f32_e32 v175, v175
	v_pk_add_f32 v[168:169], v[168:169], 1.0 op_sel_hi:[1,0]
	v_pk_add_f32 v[170:171], v[170:171], 1.0 op_sel_hi:[1,0]
	v_pk_add_f32 v[172:173], v[172:173], 1.0 op_sel_hi:[1,0]
	v_pk_add_f32 v[174:175], v[174:175], 1.0 op_sel_hi:[1,0]
	v_rcp_f32_e32 v168, v168
	v_rcp_f32_e32 v169, v169
	v_rcp_f32_e32 v170, v170
	v_rcp_f32_e32 v171, v171
	v_rcp_f32_e32 v172, v172
	v_rcp_f32_e32 v173, v173
	v_rcp_f32_e32 v174, v174
	v_rcp_f32_e32 v175, v175
	v_pk_mul_f32 v[14:15], v[14:15], v[168:169]
	v_pk_mul_f32 v[16:17], v[16:17], v[170:171]
	v_pk_mul_f32 v[6:7], v[6:7], v[172:173]
	v_pk_mul_f32 v[8:9], v[8:9], v[174:175]
	v_add_u32_e32 v182, 0xb0, v146
	v_pk_mul_f32 v[10:11], v[14:15], v[10:11]
	v_pk_mul_f32 v[12:13], v[16:17], v[12:13]
	v_pk_mul_f32 v[2:3], v[6:7], v[2:3]
	v_pk_mul_f32 v[4:5], v[8:9], v[4:5]
	v_mad_i64_i32 v[180:181], s[0:1], v182, s13, v[140:141]
	v_cvt_pk_bf16_f32 v176, v10, v11
	v_cvt_pk_bf16_f32 v177, v12, v13
	v_cvt_pk_bf16_f32 v178, v2, v3
	v_cvt_pk_bf16_f32 v179, v4, v5
	v_lshl_add_u64 v[180:181], v[180:181], 0, v[184:185]
	global_store_dwordx4 v[180:181], v[176:179], off
	s_cbranch_vccnz .LBB0_833
	s_andn2_b64 vcc, exec, s[4:5]
	s_cbranch_vccnz .LBB0_832
	s_barrier
	s_branch .LBB0_832

.LBB0_1593:
	s_ashr_i32 s19, s18, 31
	s_lshl_b64 s[0:1], s[18:19], 20
	s_add_u32 s20, s42, s0
	s_addc_u32 s21, s43, s1
	s_and_b64 s[0:1], s[8:9], exec
	s_cselect_b32 s19, s21, s5
	s_cselect_b32 s49, s20, s4
	s_ashr_i32 s17, s16, 31
	s_lshl_b64 s[0:1], s[16:17], 20
	s_add_u32 s22, s30, s0
	s_addc_u32 s23, s31, s1
	s_and_b64 s[0:1], s[8:9], exec
	s_cselect_b32 s17, s23, s3
	s_cselect_b32 s58, s22, s2
	s_add_u32 s28, s4, 0x80080
	s_addc_u32 s29, s5, 0
	s_add_u32 s59, s2, 0x100
	v_mov_b32_e32 v2, 0
	s_addc_u32 s60, s3, 0
	s_mov_b32 s61, -2
	v_mov_b32_e32 v3, v2
	v_pk_mov_b32 v[4:5], v[2:3], v[2:3] op_sel:[0,1]
	v_pk_mov_b32 v[10:11], v[2:3], v[2:3] op_sel:[0,1]
	v_pk_mov_b32 v[12:13], v[2:3], v[2:3] op_sel:[0,1]
	v_pk_mov_b32 v[18:19], v[2:3], v[2:3] op_sel:[0,1]
	v_pk_mov_b32 v[20:21], v[2:3], v[2:3] op_sel:[0,1]
	v_pk_mov_b32 v[26:27], v[2:3], v[2:3] op_sel:[0,1]
	v_pk_mov_b32 v[28:29], v[2:3], v[2:3] op_sel:[0,1]
	v_pk_mov_b32 v[34:35], v[2:3], v[2:3] op_sel:[0,1]
	v_pk_mov_b32 v[36:37], v[2:3], v[2:3] op_sel:[0,1]
	v_pk_mov_b32 v[42:43], v[2:3], v[2:3] op_sel:[0,1]
	v_pk_mov_b32 v[44:45], v[2:3], v[2:3] op_sel:[0,1]
	v_pk_mov_b32 v[50:51], v[2:3], v[2:3] op_sel:[0,1]
	v_pk_mov_b32 v[52:53], v[2:3], v[2:3] op_sel:[0,1]
	v_pk_mov_b32 v[58:59], v[2:3], v[2:3] op_sel:[0,1]
	v_pk_mov_b32 v[60:61], v[2:3], v[2:3] op_sel:[0,1]
	v_pk_mov_b32 v[6:7], v[2:3], v[2:3] op_sel:[0,1]
	v_pk_mov_b32 v[8:9], v[2:3], v[2:3] op_sel:[0,1]
	v_pk_mov_b32 v[14:15], v[2:3], v[2:3] op_sel:[0,1]
	v_pk_mov_b32 v[16:17], v[2:3], v[2:3] op_sel:[0,1]
	v_pk_mov_b32 v[22:23], v[2:3], v[2:3] op_sel:[0,1]
	v_pk_mov_b32 v[24:25], v[2:3], v[2:3] op_sel:[0,1]
	v_pk_mov_b32 v[30:31], v[2:3], v[2:3] op_sel:[0,1]
	v_pk_mov_b32 v[32:33], v[2:3], v[2:3] op_sel:[0,1]
	v_pk_mov_b32 v[38:39], v[2:3], v[2:3] op_sel:[0,1]
	v_pk_mov_b32 v[40:41], v[2:3], v[2:3] op_sel:[0,1]
	v_pk_mov_b32 v[46:47], v[2:3], v[2:3] op_sel:[0,1]
	v_pk_mov_b32 v[48:49], v[2:3], v[2:3] op_sel:[0,1]
	v_pk_mov_b32 v[54:55], v[2:3], v[2:3] op_sel:[0,1]
	v_pk_mov_b32 v[56:57], v[2:3], v[2:3] op_sel:[0,1]
	v_pk_mov_b32 v[62:63], v[2:3], v[2:3] op_sel:[0,1]
	v_pk_mov_b32 v[64:65], v[2:3], v[2:3] op_sel:[0,1]
	v_pk_mov_b32 v[66:67], v[2:3], v[2:3] op_sel:[0,1]
	v_pk_mov_b32 v[68:69], v[2:3], v[2:3] op_sel:[0,1]
	v_pk_mov_b32 v[74:75], v[2:3], v[2:3] op_sel:[0,1]
	v_pk_mov_b32 v[76:77], v[2:3], v[2:3] op_sel:[0,1]
	v_pk_mov_b32 v[82:83], v[2:3], v[2:3] op_sel:[0,1]
	v_pk_mov_b32 v[84:85], v[2:3], v[2:3] op_sel:[0,1]
	v_pk_mov_b32 v[90:91], v[2:3], v[2:3] op_sel:[0,1]
	v_pk_mov_b32 v[92:93], v[2:3], v[2:3] op_sel:[0,1]
	v_pk_mov_b32 v[98:99], v[2:3], v[2:3] op_sel:[0,1]
	v_pk_mov_b32 v[100:101], v[2:3], v[2:3] op_sel:[0,1]
	v_pk_mov_b32 v[106:107], v[2:3], v[2:3] op_sel:[0,1]
	v_pk_mov_b32 v[108:109], v[2:3], v[2:3] op_sel:[0,1]
	v_pk_mov_b32 v[114:115], v[2:3], v[2:3] op_sel:[0,1]
	v_pk_mov_b32 v[116:117], v[2:3], v[2:3] op_sel:[0,1]
	v_pk_mov_b32 v[122:123], v[2:3], v[2:3] op_sel:[0,1]
	v_pk_mov_b32 v[124:125], v[2:3], v[2:3] op_sel:[0,1]
	v_pk_mov_b32 v[70:71], v[2:3], v[2:3] op_sel:[0,1]
	v_pk_mov_b32 v[72:73], v[2:3], v[2:3] op_sel:[0,1]
	v_pk_mov_b32 v[78:79], v[2:3], v[2:3] op_sel:[0,1]
	v_pk_mov_b32 v[80:81], v[2:3], v[2:3] op_sel:[0,1]
	v_pk_mov_b32 v[86:87], v[2:3], v[2:3] op_sel:[0,1]
	v_pk_mov_b32 v[88:89], v[2:3], v[2:3] op_sel:[0,1]
	v_pk_mov_b32 v[94:95], v[2:3], v[2:3] op_sel:[0,1]
	v_pk_mov_b32 v[96:97], v[2:3], v[2:3] op_sel:[0,1]
	v_pk_mov_b32 v[102:103], v[2:3], v[2:3] op_sel:[0,1]
	v_pk_mov_b32 v[104:105], v[2:3], v[2:3] op_sel:[0,1]
	v_pk_mov_b32 v[110:111], v[2:3], v[2:3] op_sel:[0,1]
	v_pk_mov_b32 v[112:113], v[2:3], v[2:3] op_sel:[0,1]
	v_pk_mov_b32 v[118:119], v[2:3], v[2:3] op_sel:[0,1]
	v_pk_mov_b32 v[120:121], v[2:3], v[2:3] op_sel:[0,1]
	v_pk_mov_b32 v[126:127], v[2:3], v[2:3] op_sel:[0,1]
	v_pk_mov_b32 v[128:129], v[2:3], v[2:3] op_sel:[0,1]
	s_cmp_eq_u32 s101, 0x80000001
	s_cbranch_scc0 .LBB0_1594
	s_add_u32 s0, s28, 0xfff80080
	s_addc_u32 s1, s29, -1
	s_add_i32 s33, 0, 0x10000
	s_cmp_eq_u32 s61, 28
	s_cselect_b32 s5, s19, s1
	s_cselect_b32 s4, s49, s0
	s_cselect_b32 s3, s17, s60
	s_cselect_b32 s2, s58, s59
	s_add_i32 s55, 0, 0x14000
	ds_read_b128 v[146:149], v143
	ds_read_b128 v[150:153], v143 offset:1024
	ds_read_b128 v[154:157], v143 offset:2048
	ds_read_b128 v[158:161], v143 offset:3072
	ds_read_b128 v[162:165], v143 offset:16384
	ds_read_b128 v[166:169], v143 offset:17408
	ds_read_b128 v[170:173], v143 offset:18432
	ds_read_b128 v[174:177], v143 offset:19456
	s_add_i32 m0, s25, 0xc000
	ds_read_b128 v[178:181], v145
	ds_read_b128 v[182:185], v145 offset:1024
	ds_read_b128 v[186:189], v145 offset:2048
	ds_read_b128 v[190:193], v145 offset:3072
	ds_read_b128 v[194:197], v145 offset:4096
	ds_read_b128 v[198:201], v145 offset:5120
	ds_read_b128 v[208:211], v145 offset:6144
	ds_read_b128 v[212:215], v145 offset:7168
	s_add_i32 m0, s25, 0xe000
	s_nop 0
	s_waitcnt vmcnt(16)
	s_waitcnt lgkmcnt(0)
	s_setprio 1
	s_barrier
	v_mfma_f32_16x16x32_bf16 v[126:129], v[146:149], v[178:181], v[126:129]
	v_mfma_f32_16x16x32_bf16 v[118:121], v[154:157], v[178:181], v[118:121]
	v_mfma_f32_16x16x32_bf16 v[110:113], v[146:149], v[186:189], v[110:113]
	v_mfma_f32_16x16x32_bf16 v[102:105], v[154:157], v[186:189], v[102:105]
	v_mfma_f32_16x16x32_bf16 v[94:97], v[146:149], v[194:197], v[94:97]
	v_mfma_f32_16x16x32_bf16 v[86:89], v[154:157], v[194:197], v[86:89]
	v_mfma_f32_16x16x32_bf16 v[78:81], v[146:149], v[208:211], v[78:81]
	v_mfma_f32_16x16x32_bf16 v[70:73], v[154:157], v[208:211], v[70:73]
	v_mfma_f32_16x16x32_bf16 v[126:129], v[150:153], v[182:185], v[126:129]
	v_mfma_f32_16x16x32_bf16 v[118:121], v[158:161], v[182:185], v[118:121]
	v_mfma_f32_16x16x32_bf16 v[110:113], v[150:153], v[190:193], v[110:113]
	v_mfma_f32_16x16x32_bf16 v[102:105], v[158:161], v[190:193], v[102:105]
	v_mfma_f32_16x16x32_bf16 v[94:97], v[150:153], v[198:201], v[94:97]
	v_mfma_f32_16x16x32_bf16 v[86:89], v[158:161], v[198:201], v[86:89]
	v_mfma_f32_16x16x32_bf16 v[78:81], v[150:153], v[212:215], v[78:81]
	v_mfma_f32_16x16x32_bf16 v[70:73], v[158:161], v[212:215], v[70:73]
	v_mfma_f32_16x16x32_bf16 v[122:125], v[162:165], v[178:181], v[122:125]
	v_mfma_f32_16x16x32_bf16 v[114:117], v[170:173], v[178:181], v[114:117]
	v_mfma_f32_16x16x32_bf16 v[106:109], v[162:165], v[186:189], v[106:109]
	v_mfma_f32_16x16x32_bf16 v[98:101], v[170:173], v[186:189], v[98:101]
	v_mfma_f32_16x16x32_bf16 v[90:93], v[162:165], v[194:197], v[90:93]
	v_mfma_f32_16x16x32_bf16 v[82:85], v[170:173], v[194:197], v[82:85]
	v_mfma_f32_16x16x32_bf16 v[74:77], v[162:165], v[208:211], v[74:77]
	v_mfma_f32_16x16x32_bf16 v[66:69], v[170:173], v[208:211], v[66:69]
	v_mfma_f32_16x16x32_bf16 v[122:125], v[166:169], v[182:185], v[122:125]
	v_mfma_f32_16x16x32_bf16 v[114:117], v[174:177], v[182:185], v[114:117]
	v_mfma_f32_16x16x32_bf16 v[106:109], v[166:169], v[190:193], v[106:109]
	v_mfma_f32_16x16x32_bf16 v[98:101], v[174:177], v[190:193], v[98:101]
	v_mfma_f32_16x16x32_bf16 v[90:93], v[166:169], v[198:201], v[90:93]
	v_mfma_f32_16x16x32_bf16 v[82:85], v[174:177], v[198:201], v[82:85]
	v_mfma_f32_16x16x32_bf16 v[74:77], v[166:169], v[212:215], v[74:77]
	v_mfma_f32_16x16x32_bf16 v[66:69], v[174:177], v[212:215], v[66:69]
	s_barrier
	s_setprio 0
	s_add_i32 s0, s33, s36
	s_mov_b32 m0, s0
	ds_read_b128 v[178:181], v145 offset:16384
	ds_read_b128 v[182:185], v145 offset:17408
	ds_read_b128 v[186:189], v145 offset:18432
	ds_read_b128 v[190:193], v145 offset:19456
	ds_read_b128 v[194:197], v145 offset:20480
	ds_read_b128 v[198:201], v145 offset:21504
	ds_read_b128 v[208:211], v145 offset:22528
	ds_read_b128 v[212:215], v145 offset:23552
	global_load_lds_dwordx4 v202, s[2:3]
	s_add_i32 m0, s0, 0x2000
	s_add_u32 s0, s2, 0x80000
	s_addc_u32 s1, s3, 0
	s_add_i32 s33, s55, s36
	global_load_lds_dwordx4 v130, s[2:3]
	s_mov_b32 m0, s33
	s_nop 0
	global_load_lds_dwordx4 v202, s[0:1]
	s_add_i32 m0, s33, 0x2000
	s_nop 0
	global_load_lds_dwordx4 v130, s[0:1]
	s_mov_b32 m0, s25
	s_nop 0
	global_load_lds_dwordx4 v134, s[4:5]
	s_mov_b32 m0, s27
	s_nop 0
	global_load_lds_dwordx4 v132, s[4:5]
	s_waitcnt vmcnt(16)
	s_waitcnt lgkmcnt(0)
	s_setprio 1
	s_barrier
	v_mfma_f32_16x16x32_bf16 v[62:65], v[146:149], v[178:181], v[62:65]
	v_mfma_f32_16x16x32_bf16 v[54:57], v[154:157], v[178:181], v[54:57]
	v_mfma_f32_16x16x32_bf16 v[46:49], v[146:149], v[186:189], v[46:49]
	v_mfma_f32_16x16x32_bf16 v[38:41], v[154:157], v[186:189], v[38:41]
	v_mfma_f32_16x16x32_bf16 v[30:33], v[146:149], v[194:197], v[30:33]
	v_mfma_f32_16x16x32_bf16 v[22:25], v[154:157], v[194:197], v[22:25]
	v_mfma_f32_16x16x32_bf16 v[14:17], v[146:149], v[208:211], v[14:17]
	v_mfma_f32_16x16x32_bf16 v[6:9], v[154:157], v[208:211], v[6:9]
	v_mfma_f32_16x16x32_bf16 v[62:65], v[150:153], v[182:185], v[62:65]
	v_mfma_f32_16x16x32_bf16 v[54:57], v[158:161], v[182:185], v[54:57]
	v_mfma_f32_16x16x32_bf16 v[46:49], v[150:153], v[190:193], v[46:49]
	v_mfma_f32_16x16x32_bf16 v[38:41], v[158:161], v[190:193], v[38:41]
	v_mfma_f32_16x16x32_bf16 v[30:33], v[150:153], v[198:201], v[30:33]
	v_mfma_f32_16x16x32_bf16 v[22:25], v[158:161], v[198:201], v[22:25]
	v_mfma_f32_16x16x32_bf16 v[14:17], v[150:153], v[212:215], v[14:17]
	v_mfma_f32_16x16x32_bf16 v[6:9], v[158:161], v[212:215], v[6:9]
	v_mfma_f32_16x16x32_bf16 v[58:61], v[162:165], v[178:181], v[58:61]
	v_mfma_f32_16x16x32_bf16 v[50:53], v[170:173], v[178:181], v[50:53]
	v_mfma_f32_16x16x32_bf16 v[42:45], v[162:165], v[186:189], v[42:45]
	v_mfma_f32_16x16x32_bf16 v[34:37], v[170:173], v[186:189], v[34:37]
	v_mfma_f32_16x16x32_bf16 v[26:29], v[162:165], v[194:197], v[26:29]
	v_mfma_f32_16x16x32_bf16 v[18:21], v[170:173], v[194:197], v[18:21]
	v_mfma_f32_16x16x32_bf16 v[10:13], v[162:165], v[208:211], v[10:13]
	v_mfma_f32_16x16x32_bf16 v[2:5], v[170:173], v[208:211], v[2:5]
	v_mfma_f32_16x16x32_bf16 v[58:61], v[166:169], v[182:185], v[58:61]
	v_mfma_f32_16x16x32_bf16 v[50:53], v[174:177], v[182:185], v[50:53]
	v_mfma_f32_16x16x32_bf16 v[42:45], v[166:169], v[190:193], v[42:45]
	v_mfma_f32_16x16x32_bf16 v[34:37], v[174:177], v[190:193], v[34:37]
	v_mfma_f32_16x16x32_bf16 v[26:29], v[166:169], v[198:201], v[26:29]
	v_mfma_f32_16x16x32_bf16 v[18:21], v[174:177], v[198:201], v[18:21]
	v_mfma_f32_16x16x32_bf16 v[10:13], v[166:169], v[212:215], v[10:13]
	v_mfma_f32_16x16x32_bf16 v[2:5], v[174:177], v[212:215], v[2:5]
	s_barrier
	s_setprio 0
	s_add_i32 s33, 0, 0x18000
	s_add_i32 s55, 0, 0x1c000
	ds_read_b128 v[146:149], v143 offset:32768
	ds_read_b128 v[150:153], v143 offset:33792
	ds_read_b128 v[154:157], v143 offset:34816
	ds_read_b128 v[158:161], v143 offset:35840
	ds_read_b128 v[162:165], v143 offset:49152
	ds_read_b128 v[166:169], v143 offset:50176
	ds_read_b128 v[170:173], v143 offset:51200
	ds_read_b128 v[174:177], v143 offset:52224
	s_add_u32 s0, s4, 0x80000
	s_addc_u32 s1, s5, 0
	s_mov_b32 m0, s37
	ds_read_b128 v[178:181], v145 offset:32768
	ds_read_b128 v[182:185], v145 offset:33792
	ds_read_b128 v[186:189], v145 offset:34816
	ds_read_b128 v[190:193], v145 offset:35840
	ds_read_b128 v[194:197], v145 offset:36864
	ds_read_b128 v[198:201], v145 offset:37888
	ds_read_b128 v[208:211], v145 offset:38912
	ds_read_b128 v[212:215], v145 offset:39936
	global_load_lds_dwordx4 v134, s[0:1]
	s_mov_b32 m0, s38
	s_nop 0
	global_load_lds_dwordx4 v132, s[0:1]
	s_waitcnt vmcnt(16)
	s_waitcnt lgkmcnt(0)
	s_setprio 1
	s_barrier
	v_mfma_f32_16x16x32_bf16 v[126:129], v[146:149], v[178:181], v[126:129]
	v_mfma_f32_16x16x32_bf16 v[118:121], v[154:157], v[178:181], v[118:121]
	v_mfma_f32_16x16x32_bf16 v[110:113], v[146:149], v[186:189], v[110:113]
	v_mfma_f32_16x16x32_bf16 v[102:105], v[154:157], v[186:189], v[102:105]
	v_mfma_f32_16x16x32_bf16 v[94:97], v[146:149], v[194:197], v[94:97]
	v_mfma_f32_16x16x32_bf16 v[86:89], v[154:157], v[194:197], v[86:89]
	v_mfma_f32_16x16x32_bf16 v[78:81], v[146:149], v[208:211], v[78:81]
	v_mfma_f32_16x16x32_bf16 v[70:73], v[154:157], v[208:211], v[70:73]
	v_mfma_f32_16x16x32_bf16 v[126:129], v[150:153], v[182:185], v[126:129]
	v_mfma_f32_16x16x32_bf16 v[118:121], v[158:161], v[182:185], v[118:121]
	v_mfma_f32_16x16x32_bf16 v[110:113], v[150:153], v[190:193], v[110:113]
	v_mfma_f32_16x16x32_bf16 v[102:105], v[158:161], v[190:193], v[102:105]
	v_mfma_f32_16x16x32_bf16 v[94:97], v[150:153], v[198:201], v[94:97]
	v_mfma_f32_16x16x32_bf16 v[86:89], v[158:161], v[198:201], v[86:89]
	v_mfma_f32_16x16x32_bf16 v[78:81], v[150:153], v[212:215], v[78:81]
	v_mfma_f32_16x16x32_bf16 v[70:73], v[158:161], v[212:215], v[70:73]
	v_mfma_f32_16x16x32_bf16 v[122:125], v[162:165], v[178:181], v[122:125]
	v_mfma_f32_16x16x32_bf16 v[114:117], v[170:173], v[178:181], v[114:117]
	v_mfma_f32_16x16x32_bf16 v[106:109], v[162:165], v[186:189], v[106:109]
	v_mfma_f32_16x16x32_bf16 v[98:101], v[170:173], v[186:189], v[98:101]
	v_mfma_f32_16x16x32_bf16 v[90:93], v[162:165], v[194:197], v[90:93]
	v_mfma_f32_16x16x32_bf16 v[82:85], v[170:173], v[194:197], v[82:85]
	v_mfma_f32_16x16x32_bf16 v[74:77], v[162:165], v[208:211], v[74:77]
	v_mfma_f32_16x16x32_bf16 v[66:69], v[170:173], v[208:211], v[66:69]
	v_mfma_f32_16x16x32_bf16 v[122:125], v[166:169], v[182:185], v[122:125]
	v_mfma_f32_16x16x32_bf16 v[114:117], v[174:177], v[182:185], v[114:117]
	v_mfma_f32_16x16x32_bf16 v[106:109], v[166:169], v[190:193], v[106:109]
	v_mfma_f32_16x16x32_bf16 v[98:101], v[174:177], v[190:193], v[98:101]
	v_mfma_f32_16x16x32_bf16 v[90:93], v[166:169], v[198:201], v[90:93]
	v_mfma_f32_16x16x32_bf16 v[82:85], v[174:177], v[198:201], v[82:85]
	v_mfma_f32_16x16x32_bf16 v[74:77], v[166:169], v[212:215], v[74:77]
	v_mfma_f32_16x16x32_bf16 v[66:69], v[174:177], v[212:215], v[66:69]
	s_barrier
	s_setprio 0
	s_branch .Lpeel_mid_10
.LBB0_1594:
	s_add_u32 s0, s28, 0xfff80080
	s_addc_u32 s1, s29, -1
	s_add_i32 s33, 0, 0x10000
	s_cmp_eq_u32 s61, 28
	s_cselect_b32 s5, s19, s1
	s_cselect_b32 s4, s49, s0
	s_cselect_b32 s3, s17, s60
	s_cselect_b32 s2, s58, s59
	s_add_i32 s55, 0, 0x14000
	ds_read_b128 v[146:149], v143
	ds_read_b128 v[150:153], v143 offset:1024
	ds_read_b128 v[154:157], v143 offset:2048
	ds_read_b128 v[158:161], v143 offset:3072
	ds_read_b128 v[162:165], v143 offset:16384
	ds_read_b128 v[166:169], v143 offset:17408
	ds_read_b128 v[170:173], v143 offset:18432
	ds_read_b128 v[174:177], v143 offset:19456
	s_add_i32 m0, s25, 0xc000
	ds_read_b128 v[178:181], v145
	ds_read_b128 v[182:185], v145 offset:1024
	ds_read_b128 v[186:189], v145 offset:2048
	ds_read_b128 v[190:193], v145 offset:3072
	ds_read_b128 v[194:197], v145 offset:4096
	ds_read_b128 v[198:201], v145 offset:5120
	ds_read_b128 v[208:211], v145 offset:6144
	ds_read_b128 v[212:215], v145 offset:7168
	global_load_lds_dwordx4 v136, s[28:29]
	s_add_i32 m0, s25, 0xe000
	s_nop 0
	global_load_lds_dwordx4 v138, s[28:29]
	s_waitcnt vmcnt(8)
	s_waitcnt lgkmcnt(0)
	s_setprio 1
	s_barrier
	v_mfma_f32_16x16x32_bf16 v[126:129], v[146:149], v[178:181], v[126:129]
	v_mfma_f32_16x16x32_bf16 v[118:121], v[154:157], v[178:181], v[118:121]
	v_mfma_f32_16x16x32_bf16 v[110:113], v[146:149], v[186:189], v[110:113]
	v_mfma_f32_16x16x32_bf16 v[102:105], v[154:157], v[186:189], v[102:105]
	v_mfma_f32_16x16x32_bf16 v[94:97], v[146:149], v[194:197], v[94:97]
	v_mfma_f32_16x16x32_bf16 v[86:89], v[154:157], v[194:197], v[86:89]
	v_mfma_f32_16x16x32_bf16 v[78:81], v[146:149], v[208:211], v[78:81]
	v_mfma_f32_16x16x32_bf16 v[70:73], v[154:157], v[208:211], v[70:73]
	v_mfma_f32_16x16x32_bf16 v[126:129], v[150:153], v[182:185], v[126:129]
	v_mfma_f32_16x16x32_bf16 v[118:121], v[158:161], v[182:185], v[118:121]
	v_mfma_f32_16x16x32_bf16 v[110:113], v[150:153], v[190:193], v[110:113]
	v_mfma_f32_16x16x32_bf16 v[102:105], v[158:161], v[190:193], v[102:105]
	v_mfma_f32_16x16x32_bf16 v[94:97], v[150:153], v[198:201], v[94:97]
	v_mfma_f32_16x16x32_bf16 v[86:89], v[158:161], v[198:201], v[86:89]
	v_mfma_f32_16x16x32_bf16 v[78:81], v[150:153], v[212:215], v[78:81]
	v_mfma_f32_16x16x32_bf16 v[70:73], v[158:161], v[212:215], v[70:73]
	v_mfma_f32_16x16x32_bf16 v[122:125], v[162:165], v[178:181], v[122:125]
	v_mfma_f32_16x16x32_bf16 v[114:117], v[170:173], v[178:181], v[114:117]
	v_mfma_f32_16x16x32_bf16 v[106:109], v[162:165], v[186:189], v[106:109]
	v_mfma_f32_16x16x32_bf16 v[98:101], v[170:173], v[186:189], v[98:101]
	v_mfma_f32_16x16x32_bf16 v[90:93], v[162:165], v[194:197], v[90:93]
	v_mfma_f32_16x16x32_bf16 v[82:85], v[170:173], v[194:197], v[82:85]
	v_mfma_f32_16x16x32_bf16 v[74:77], v[162:165], v[208:211], v[74:77]
	v_mfma_f32_16x16x32_bf16 v[66:69], v[170:173], v[208:211], v[66:69]
	v_mfma_f32_16x16x32_bf16 v[122:125], v[166:169], v[182:185], v[122:125]
	v_mfma_f32_16x16x32_bf16 v[114:117], v[174:177], v[182:185], v[114:117]
	v_mfma_f32_16x16x32_bf16 v[106:109], v[166:169], v[190:193], v[106:109]
	v_mfma_f32_16x16x32_bf16 v[98:101], v[174:177], v[190:193], v[98:101]
	v_mfma_f32_16x16x32_bf16 v[90:93], v[166:169], v[198:201], v[90:93]
	v_mfma_f32_16x16x32_bf16 v[82:85], v[174:177], v[198:201], v[82:85]
	v_mfma_f32_16x16x32_bf16 v[74:77], v[166:169], v[212:215], v[74:77]
	v_mfma_f32_16x16x32_bf16 v[66:69], v[174:177], v[212:215], v[66:69]
	s_barrier
	s_setprio 0
	s_add_i32 s0, s33, s36
	s_mov_b32 m0, s0
	ds_read_b128 v[178:181], v145 offset:16384
	ds_read_b128 v[182:185], v145 offset:17408
	ds_read_b128 v[186:189], v145 offset:18432
	ds_read_b128 v[190:193], v145 offset:19456
	ds_read_b128 v[194:197], v145 offset:20480
	ds_read_b128 v[198:201], v145 offset:21504
	ds_read_b128 v[208:211], v145 offset:22528
	ds_read_b128 v[212:215], v145 offset:23552
	global_load_lds_dwordx4 v202, s[2:3]
	s_add_i32 m0, s0, 0x2000
	s_add_u32 s0, s2, 0x80000
	s_addc_u32 s1, s3, 0
	s_add_i32 s33, s55, s36
	global_load_lds_dwordx4 v130, s[2:3]
	s_mov_b32 m0, s33
	s_nop 0
	global_load_lds_dwordx4 v202, s[0:1]
	s_add_i32 m0, s33, 0x2000
	s_nop 0
	global_load_lds_dwordx4 v130, s[0:1]
	s_mov_b32 m0, s25
	s_nop 0
	global_load_lds_dwordx4 v134, s[4:5]
	s_mov_b32 m0, s27
	s_nop 0
	global_load_lds_dwordx4 v132, s[4:5]
	s_waitcnt vmcnt(8)
	s_waitcnt lgkmcnt(0)
	s_setprio 1
	s_barrier
	v_mfma_f32_16x16x32_bf16 v[62:65], v[146:149], v[178:181], v[62:65]
	v_mfma_f32_16x16x32_bf16 v[54:57], v[154:157], v[178:181], v[54:57]
	v_mfma_f32_16x16x32_bf16 v[46:49], v[146:149], v[186:189], v[46:49]
	v_mfma_f32_16x16x32_bf16 v[38:41], v[154:157], v[186:189], v[38:41]
	v_mfma_f32_16x16x32_bf16 v[30:33], v[146:149], v[194:197], v[30:33]
	v_mfma_f32_16x16x32_bf16 v[22:25], v[154:157], v[194:197], v[22:25]
	v_mfma_f32_16x16x32_bf16 v[14:17], v[146:149], v[208:211], v[14:17]
	v_mfma_f32_16x16x32_bf16 v[6:9], v[154:157], v[208:211], v[6:9]
	v_mfma_f32_16x16x32_bf16 v[62:65], v[150:153], v[182:185], v[62:65]
	v_mfma_f32_16x16x32_bf16 v[54:57], v[158:161], v[182:185], v[54:57]
	v_mfma_f32_16x16x32_bf16 v[46:49], v[150:153], v[190:193], v[46:49]
	v_mfma_f32_16x16x32_bf16 v[38:41], v[158:161], v[190:193], v[38:41]
	v_mfma_f32_16x16x32_bf16 v[30:33], v[150:153], v[198:201], v[30:33]
	v_mfma_f32_16x16x32_bf16 v[22:25], v[158:161], v[198:201], v[22:25]
	v_mfma_f32_16x16x32_bf16 v[14:17], v[150:153], v[212:215], v[14:17]
	v_mfma_f32_16x16x32_bf16 v[6:9], v[158:161], v[212:215], v[6:9]
	v_mfma_f32_16x16x32_bf16 v[58:61], v[162:165], v[178:181], v[58:61]
	v_mfma_f32_16x16x32_bf16 v[50:53], v[170:173], v[178:181], v[50:53]
	v_mfma_f32_16x16x32_bf16 v[42:45], v[162:165], v[186:189], v[42:45]
	v_mfma_f32_16x16x32_bf16 v[34:37], v[170:173], v[186:189], v[34:37]
	v_mfma_f32_16x16x32_bf16 v[26:29], v[162:165], v[194:197], v[26:29]
	v_mfma_f32_16x16x32_bf16 v[18:21], v[170:173], v[194:197], v[18:21]
	v_mfma_f32_16x16x32_bf16 v[10:13], v[162:165], v[208:211], v[10:13]
	v_mfma_f32_16x16x32_bf16 v[2:5], v[170:173], v[208:211], v[2:5]
	v_mfma_f32_16x16x32_bf16 v[58:61], v[166:169], v[182:185], v[58:61]
	v_mfma_f32_16x16x32_bf16 v[50:53], v[174:177], v[182:185], v[50:53]
	v_mfma_f32_16x16x32_bf16 v[42:45], v[166:169], v[190:193], v[42:45]
	v_mfma_f32_16x16x32_bf16 v[34:37], v[174:177], v[190:193], v[34:37]
	v_mfma_f32_16x16x32_bf16 v[26:29], v[166:169], v[198:201], v[26:29]
	v_mfma_f32_16x16x32_bf16 v[18:21], v[174:177], v[198:201], v[18:21]
	v_mfma_f32_16x16x32_bf16 v[10:13], v[166:169], v[212:215], v[10:13]
	v_mfma_f32_16x16x32_bf16 v[2:5], v[174:177], v[212:215], v[2:5]
	s_barrier
	s_setprio 0
	s_add_i32 s33, 0, 0x18000
	s_add_i32 s55, 0, 0x1c000
	ds_read_b128 v[146:149], v143 offset:32768
	ds_read_b128 v[150:153], v143 offset:33792
	ds_read_b128 v[154:157], v143 offset:34816
	ds_read_b128 v[158:161], v143 offset:35840
	ds_read_b128 v[162:165], v143 offset:49152
	ds_read_b128 v[166:169], v143 offset:50176
	ds_read_b128 v[170:173], v143 offset:51200
	ds_read_b128 v[174:177], v143 offset:52224
	s_add_u32 s0, s4, 0x80000
	s_addc_u32 s1, s5, 0
	s_mov_b32 m0, s37
	ds_read_b128 v[178:181], v145 offset:32768
	ds_read_b128 v[182:185], v145 offset:33792
	ds_read_b128 v[186:189], v145 offset:34816
	ds_read_b128 v[190:193], v145 offset:35840
	ds_read_b128 v[194:197], v145 offset:36864
	ds_read_b128 v[198:201], v145 offset:37888
	ds_read_b128 v[208:211], v145 offset:38912
	ds_read_b128 v[212:215], v145 offset:39936
	global_load_lds_dwordx4 v134, s[0:1]
	s_mov_b32 m0, s38
	s_nop 0
	global_load_lds_dwordx4 v132, s[0:1]
	s_waitcnt vmcnt(8)
	s_waitcnt lgkmcnt(0)
	s_setprio 1
	s_barrier
	v_mfma_f32_16x16x32_bf16 v[126:129], v[146:149], v[178:181], v[126:129]
	v_mfma_f32_16x16x32_bf16 v[118:121], v[154:157], v[178:181], v[118:121]
	v_mfma_f32_16x16x32_bf16 v[110:113], v[146:149], v[186:189], v[110:113]
	v_mfma_f32_16x16x32_bf16 v[102:105], v[154:157], v[186:189], v[102:105]
	v_mfma_f32_16x16x32_bf16 v[94:97], v[146:149], v[194:197], v[94:97]
	v_mfma_f32_16x16x32_bf16 v[86:89], v[154:157], v[194:197], v[86:89]
	v_mfma_f32_16x16x32_bf16 v[78:81], v[146:149], v[208:211], v[78:81]
	v_mfma_f32_16x16x32_bf16 v[70:73], v[154:157], v[208:211], v[70:73]
	v_mfma_f32_16x16x32_bf16 v[126:129], v[150:153], v[182:185], v[126:129]
	v_mfma_f32_16x16x32_bf16 v[118:121], v[158:161], v[182:185], v[118:121]
	v_mfma_f32_16x16x32_bf16 v[110:113], v[150:153], v[190:193], v[110:113]
	v_mfma_f32_16x16x32_bf16 v[102:105], v[158:161], v[190:193], v[102:105]
	v_mfma_f32_16x16x32_bf16 v[94:97], v[150:153], v[198:201], v[94:97]
	v_mfma_f32_16x16x32_bf16 v[86:89], v[158:161], v[198:201], v[86:89]
	v_mfma_f32_16x16x32_bf16 v[78:81], v[150:153], v[212:215], v[78:81]
	v_mfma_f32_16x16x32_bf16 v[70:73], v[158:161], v[212:215], v[70:73]
	v_mfma_f32_16x16x32_bf16 v[122:125], v[162:165], v[178:181], v[122:125]
	v_mfma_f32_16x16x32_bf16 v[114:117], v[170:173], v[178:181], v[114:117]
	v_mfma_f32_16x16x32_bf16 v[106:109], v[162:165], v[186:189], v[106:109]
	v_mfma_f32_16x16x32_bf16 v[98:101], v[170:173], v[186:189], v[98:101]
	v_mfma_f32_16x16x32_bf16 v[90:93], v[162:165], v[194:197], v[90:93]
	v_mfma_f32_16x16x32_bf16 v[82:85], v[170:173], v[194:197], v[82:85]
	v_mfma_f32_16x16x32_bf16 v[74:77], v[162:165], v[208:211], v[74:77]
	v_mfma_f32_16x16x32_bf16 v[66:69], v[170:173], v[208:211], v[66:69]
	v_mfma_f32_16x16x32_bf16 v[122:125], v[166:169], v[182:185], v[122:125]
	v_mfma_f32_16x16x32_bf16 v[114:117], v[174:177], v[182:185], v[114:117]
	v_mfma_f32_16x16x32_bf16 v[106:109], v[166:169], v[190:193], v[106:109]
	v_mfma_f32_16x16x32_bf16 v[98:101], v[174:177], v[190:193], v[98:101]
	v_mfma_f32_16x16x32_bf16 v[90:93], v[166:169], v[198:201], v[90:93]
	v_mfma_f32_16x16x32_bf16 v[82:85], v[174:177], v[198:201], v[82:85]
	v_mfma_f32_16x16x32_bf16 v[74:77], v[166:169], v[212:215], v[74:77]
	v_mfma_f32_16x16x32_bf16 v[66:69], v[174:177], v[212:215], v[66:69]
	s_barrier
	s_setprio 0
.Lpeel_mid_10:
	s_add_i32 s0, s33, s36
	s_add_u32 s100, s2, 0x80
	s_addc_u32 s101, s3, 0
	s_mov_b32 m0, s0
	ds_read_b128 v[178:181], v145 offset:49152
	ds_read_b128 v[182:185], v145 offset:50176
	ds_read_b128 v[186:189], v145 offset:51200
	ds_read_b128 v[190:193], v145 offset:52224
	ds_read_b128 v[194:197], v145 offset:53248
	ds_read_b128 v[198:201], v145 offset:54272
	ds_read_b128 v[208:211], v145 offset:55296
	ds_read_b128 v[212:215], v145 offset:56320
	global_load_lds_dwordx4 v202, s[100:101]
	s_add_i32 m0, s0, 0x2000
	s_add_u32 s100, s2, 0x80
	s_addc_u32 s101, s3, 0
	s_add_u32 s0, s2, 0x80080
	s_addc_u32 s1, s3, 0
	s_add_i32 s2, s55, s36
	global_load_lds_dwordx4 v130, s[100:101]
	s_mov_b32 m0, s2
	s_nop 0
	global_load_lds_dwordx4 v202, s[0:1]
	s_add_i32 m0, s2, 0x2000
	s_nop 0
	global_load_lds_dwordx4 v130, s[0:1]
	s_add_u32 s100, s4, 0x80
	s_addc_u32 s101, s5, 0
	s_mov_b32 m0, s39
	s_nop 0
	global_load_lds_dwordx4 v134, s[100:101]
	s_add_u32 s100, s4, 0x80
	s_addc_u32 s101, s5, 0
	s_mov_b32 m0, s40
	s_nop 0
	global_load_lds_dwordx4 v132, s[100:101]
	s_waitcnt vmcnt(8)
	s_waitcnt lgkmcnt(0)
	s_setprio 1
	s_barrier
	v_mfma_f32_16x16x32_bf16 v[62:65], v[146:149], v[178:181], v[62:65]
	v_mfma_f32_16x16x32_bf16 v[54:57], v[154:157], v[178:181], v[54:57]
	v_mfma_f32_16x16x32_bf16 v[46:49], v[146:149], v[186:189], v[46:49]
	v_mfma_f32_16x16x32_bf16 v[38:41], v[154:157], v[186:189], v[38:41]
	v_mfma_f32_16x16x32_bf16 v[30:33], v[146:149], v[194:197], v[30:33]
	v_mfma_f32_16x16x32_bf16 v[22:25], v[154:157], v[194:197], v[22:25]
	v_mfma_f32_16x16x32_bf16 v[14:17], v[146:149], v[208:211], v[14:17]
	v_mfma_f32_16x16x32_bf16 v[6:9], v[154:157], v[208:211], v[6:9]
	v_mfma_f32_16x16x32_bf16 v[62:65], v[150:153], v[182:185], v[62:65]
	v_mfma_f32_16x16x32_bf16 v[54:57], v[158:161], v[182:185], v[54:57]
	v_mfma_f32_16x16x32_bf16 v[46:49], v[150:153], v[190:193], v[46:49]
	v_mfma_f32_16x16x32_bf16 v[38:41], v[158:161], v[190:193], v[38:41]
	v_mfma_f32_16x16x32_bf16 v[30:33], v[150:153], v[198:201], v[30:33]
	v_mfma_f32_16x16x32_bf16 v[22:25], v[158:161], v[198:201], v[22:25]
	v_mfma_f32_16x16x32_bf16 v[14:17], v[150:153], v[212:215], v[14:17]
	v_mfma_f32_16x16x32_bf16 v[6:9], v[158:161], v[212:215], v[6:9]
	v_mfma_f32_16x16x32_bf16 v[58:61], v[162:165], v[178:181], v[58:61]
	v_mfma_f32_16x16x32_bf16 v[50:53], v[170:173], v[178:181], v[50:53]
	v_mfma_f32_16x16x32_bf16 v[42:45], v[162:165], v[186:189], v[42:45]
	v_mfma_f32_16x16x32_bf16 v[34:37], v[170:173], v[186:189], v[34:37]
	v_mfma_f32_16x16x32_bf16 v[26:29], v[162:165], v[194:197], v[26:29]
	v_mfma_f32_16x16x32_bf16 v[18:21], v[170:173], v[194:197], v[18:21]
	v_mfma_f32_16x16x32_bf16 v[10:13], v[162:165], v[208:211], v[10:13]
	v_mfma_f32_16x16x32_bf16 v[2:5], v[170:173], v[208:211], v[2:5]
	v_mfma_f32_16x16x32_bf16 v[58:61], v[166:169], v[182:185], v[58:61]
	v_mfma_f32_16x16x32_bf16 v[50:53], v[174:177], v[182:185], v[50:53]
	v_mfma_f32_16x16x32_bf16 v[42:45], v[166:169], v[190:193], v[42:45]
	v_mfma_f32_16x16x32_bf16 v[34:37], v[174:177], v[190:193], v[34:37]
	v_mfma_f32_16x16x32_bf16 v[26:29], v[166:169], v[198:201], v[26:29]
	v_mfma_f32_16x16x32_bf16 v[18:21], v[174:177], v[198:201], v[18:21]
	v_mfma_f32_16x16x32_bf16 v[10:13], v[166:169], v[212:215], v[10:13]
	v_mfma_f32_16x16x32_bf16 v[2:5], v[174:177], v[212:215], v[2:5]
	s_barrier
	s_setprio 0
	s_add_i32 s61, s61, 2
	s_add_u32 s28, s28, 0x100
	s_addc_u32 s29, s29, 0
	s_add_u32 s59, s59, 0x100
	s_addc_u32 s60, s60, 0
	s_cmp_gt_u32 s61, 29
	s_cbranch_scc0 .LBB0_1594
	s_and_b64 vcc, exec, s[14:15]
	s_cbranch_vccz .LBB0_1597
	s_barrier
.LBB0_1597:
	s_add_u32 s100, s49, 0x80080
	s_addc_u32 s101, s19, 0
	s_add_i32 m0, s25, 0xc000
	s_nop 0
	global_load_lds_dwordx4 v136, s[100:101]
	s_add_i32 m0, s25, 0xe000
	s_nop 0
	global_load_lds_dwordx4 v138, s[100:101]
	s_mov_b32 s101, 0x80000001
	v_lshl_or_b32 v148, s24, 7, v144
	v_lshl_add_u32 v146, s26, 8, v142
	v_ashrrev_i32_e32 v149, 31, v148
	v_mov_b64_e32 v[140:141], s[78:79]
	v_mad_i64_i32 v[150:151], s[0:1], v146, s13, v[140:141]
	s_mov_b64 s[2:3], -1
	s_andn2_b64 vcc, exec, s[8:9]
	s_mov_b32 s100, 0xbfb8aa3b
	v_lshlrev_b64 v[184:185], 1, v[148:149]
	v_pk_mul_f32 v[152:153], v[126:127], s[100:101] op_sel_hi:[1,0]
	v_pk_mul_f32 v[154:155], v[128:129], s[100:101] op_sel_hi:[1,0]
	v_pk_mul_f32 v[156:157], v[118:119], s[100:101] op_sel_hi:[1,0]
	v_pk_mul_f32 v[158:159], v[120:121], s[100:101] op_sel_hi:[1,0]
	v_exp_f32_e32 v152, v152
	v_exp_f32_e32 v153, v153
	v_exp_f32_e32 v154, v154
	v_exp_f32_e32 v155, v155
	v_exp_f32_e32 v156, v156
	v_exp_f32_e32 v157, v157
	v_exp_f32_e32 v158, v158
	v_exp_f32_e32 v159, v159
	v_pk_add_f32 v[152:153], v[152:153], 1.0 op_sel_hi:[1,0]
	v_pk_add_f32 v[154:155], v[154:155], 1.0 op_sel_hi:[1,0]
	v_pk_add_f32 v[156:157], v[156:157], 1.0 op_sel_hi:[1,0]
	v_pk_add_f32 v[158:159], v[158:159], 1.0 op_sel_hi:[1,0]
	v_rcp_f32_e32 v152, v152
	v_rcp_f32_e32 v153, v153
	v_rcp_f32_e32 v154, v154
	v_rcp_f32_e32 v155, v155
	v_rcp_f32_e32 v156, v156
	v_rcp_f32_e32 v157, v157
	v_rcp_f32_e32 v158, v158
	v_rcp_f32_e32 v159, v159
	v_pk_mul_f32 v[126:127], v[126:127], v[152:153]
	v_pk_mul_f32 v[128:129], v[128:129], v[154:155]
	v_pk_mul_f32 v[118:119], v[118:119], v[156:157]
	v_pk_mul_f32 v[120:121], v[120:121], v[158:159]
	v_lshl_add_u64 v[164:165], v[150:151], 0, v[184:185]
	v_pk_mul_f32 v[122:123], v[126:127], v[122:123]
	v_pk_mul_f32 v[124:125], v[128:129], v[124:125]
	v_pk_mul_f32 v[114:115], v[118:119], v[114:115]
	v_pk_mul_f32 v[116:117], v[120:121], v[116:117]
	v_cvt_pk_bf16_f32 v160, v122, v123
	v_cvt_pk_bf16_f32 v161, v124, v125
	v_cvt_pk_bf16_f32 v162, v114, v115
	v_cvt_pk_bf16_f32 v163, v116, v117
	s_nop 0
	global_store_dwordx4 v[164:165], v[160:163], off
	v_pk_mul_f32 v[168:169], v[110:111], s[100:101] op_sel_hi:[1,0]
	v_pk_mul_f32 v[170:171], v[112:113], s[100:101] op_sel_hi:[1,0]
	v_pk_mul_f32 v[172:173], v[102:103], s[100:101] op_sel_hi:[1,0]
	v_pk_mul_f32 v[174:175], v[104:105], s[100:101] op_sel_hi:[1,0]
	v_exp_f32_e32 v168, v168
	v_exp_f32_e32 v169, v169
	v_exp_f32_e32 v170, v170
	v_exp_f32_e32 v171, v171
	v_exp_f32_e32 v172, v172
	v_exp_f32_e32 v173, v173
	v_exp_f32_e32 v174, v174
	v_exp_f32_e32 v175, v175
	v_pk_add_f32 v[168:169], v[168:169], 1.0 op_sel_hi:[1,0]
	v_pk_add_f32 v[170:171], v[170:171], 1.0 op_sel_hi:[1,0]
	v_pk_add_f32 v[172:173], v[172:173], 1.0 op_sel_hi:[1,0]
	v_pk_add_f32 v[174:175], v[174:175], 1.0 op_sel_hi:[1,0]
	v_rcp_f32_e32 v168, v168
	v_rcp_f32_e32 v169, v169
	v_rcp_f32_e32 v170, v170
	v_rcp_f32_e32 v171, v171
	v_rcp_f32_e32 v172, v172
	v_rcp_f32_e32 v173, v173
	v_rcp_f32_e32 v174, v174
	v_rcp_f32_e32 v175, v175
	v_pk_mul_f32 v[110:111], v[110:111], v[168:169]
	v_pk_mul_f32 v[112:113], v[112:113], v[170:171]
	v_pk_mul_f32 v[102:103], v[102:103], v[172:173]
	v_pk_mul_f32 v[104:105], v[104:105], v[174:175]
	v_or_b32_e32 v182, 16, v146
	v_pk_mul_f32 v[106:107], v[110:111], v[106:107]
	v_pk_mul_f32 v[108:109], v[112:113], v[108:109]
	v_pk_mul_f32 v[98:99], v[102:103], v[98:99]
	v_pk_mul_f32 v[100:101], v[104:105], v[100:101]
	v_mad_i64_i32 v[180:181], s[0:1], v182, s13, v[140:141]
	v_cvt_pk_bf16_f32 v176, v106, v107
	v_cvt_pk_bf16_f32 v177, v108, v109
	v_cvt_pk_bf16_f32 v178, v98, v99
	v_cvt_pk_bf16_f32 v179, v100, v101
	v_lshl_add_u64 v[180:181], v[180:181], 0, v[184:185]
	global_store_dwordx4 v[180:181], v[176:179], off
	v_pk_mul_f32 v[152:153], v[94:95], s[100:101] op_sel_hi:[1,0]
	v_pk_mul_f32 v[154:155], v[96:97], s[100:101] op_sel_hi:[1,0]
	v_pk_mul_f32 v[156:157], v[86:87], s[100:101] op_sel_hi:[1,0]
	v_pk_mul_f32 v[158:159], v[88:89], s[100:101] op_sel_hi:[1,0]
	v_exp_f32_e32 v152, v152
	v_exp_f32_e32 v153, v153
	v_exp_f32_e32 v154, v154
	v_exp_f32_e32 v155, v155
	v_exp_f32_e32 v156, v156
	v_exp_f32_e32 v157, v157
	v_exp_f32_e32 v158, v158
	v_exp_f32_e32 v159, v159
	v_pk_add_f32 v[152:153], v[152:153], 1.0 op_sel_hi:[1,0]
	v_pk_add_f32 v[154:155], v[154:155], 1.0 op_sel_hi:[1,0]
	v_pk_add_f32 v[156:157], v[156:157], 1.0 op_sel_hi:[1,0]
	v_pk_add_f32 v[158:159], v[158:159], 1.0 op_sel_hi:[1,0]
	v_rcp_f32_e32 v152, v152
	v_rcp_f32_e32 v153, v153
	v_rcp_f32_e32 v154, v154
	v_rcp_f32_e32 v155, v155
	v_rcp_f32_e32 v156, v156
	v_rcp_f32_e32 v157, v157
	v_rcp_f32_e32 v158, v158
	v_rcp_f32_e32 v159, v159
	v_pk_mul_f32 v[94:95], v[94:95], v[152:153]
	v_pk_mul_f32 v[96:97], v[96:97], v[154:155]
	v_pk_mul_f32 v[86:87], v[86:87], v[156:157]
	v_pk_mul_f32 v[88:89], v[88:89], v[158:159]
	v_or_b32_e32 v166, 32, v146
	v_pk_mul_f32 v[90:91], v[94:95], v[90:91]
	v_pk_mul_f32 v[92:93], v[96:97], v[92:93]
	v_pk_mul_f32 v[82:83], v[86:87], v[82:83]
	v_pk_mul_f32 v[84:85], v[88:89], v[84:85]
	v_mad_i64_i32 v[164:165], s[0:1], v166, s13, v[140:141]
	v_cvt_pk_bf16_f32 v160, v90, v91
	v_cvt_pk_bf16_f32 v161, v92, v93
	v_cvt_pk_bf16_f32 v162, v82, v83
	v_cvt_pk_bf16_f32 v163, v84, v85
	v_lshl_add_u64 v[164:165], v[164:165], 0, v[184:185]
	global_store_dwordx4 v[164:165], v[160:163], off
	v_pk_mul_f32 v[168:169], v[78:79], s[100:101] op_sel_hi:[1,0]
	v_pk_mul_f32 v[170:171], v[80:81], s[100:101] op_sel_hi:[1,0]
	v_pk_mul_f32 v[172:173], v[70:71], s[100:101] op_sel_hi:[1,0]
	v_pk_mul_f32 v[174:175], v[72:73], s[100:101] op_sel_hi:[1,0]
	v_exp_f32_e32 v168, v168
	v_exp_f32_e32 v169, v169
	v_exp_f32_e32 v170, v170
	v_exp_f32_e32 v171, v171
	v_exp_f32_e32 v172, v172
	v_exp_f32_e32 v173, v173
	v_exp_f32_e32 v174, v174
	v_exp_f32_e32 v175, v175
	v_pk_add_f32 v[168:169], v[168:169], 1.0 op_sel_hi:[1,0]
	v_pk_add_f32 v[170:171], v[170:171], 1.0 op_sel_hi:[1,0]
	v_pk_add_f32 v[172:173], v[172:173], 1.0 op_sel_hi:[1,0]
	v_pk_add_f32 v[174:175], v[174:175], 1.0 op_sel_hi:[1,0]
	v_rcp_f32_e32 v168, v168
	v_rcp_f32_e32 v169, v169
	v_rcp_f32_e32 v170, v170
	v_rcp_f32_e32 v171, v171
	v_rcp_f32_e32 v172, v172
	v_rcp_f32_e32 v173, v173
	v_rcp_f32_e32 v174, v174
	v_rcp_f32_e32 v175, v175
	v_pk_mul_f32 v[78:79], v[78:79], v[168:169]
	v_pk_mul_f32 v[80:81], v[80:81], v[170:171]
	v_pk_mul_f32 v[70:71], v[70:71], v[172:173]
	v_pk_mul_f32 v[72:73], v[72:73], v[174:175]
	v_or_b32_e32 v182, 48, v146
	v_pk_mul_f32 v[74:75], v[78:79], v[74:75]
	v_pk_mul_f32 v[76:77], v[80:81], v[76:77]
	v_pk_mul_f32 v[66:67], v[70:71], v[66:67]
	v_pk_mul_f32 v[68:69], v[72:73], v[68:69]
	v_mad_i64_i32 v[180:181], s[0:1], v182, s13, v[140:141]
	v_cvt_pk_bf16_f32 v176, v74, v75
	v_cvt_pk_bf16_f32 v177, v76, v77
	v_cvt_pk_bf16_f32 v178, v66, v67
	v_cvt_pk_bf16_f32 v179, v68, v69
	v_lshl_add_u64 v[180:181], v[180:181], 0, v[184:185]
	global_store_dwordx4 v[180:181], v[176:179], off
	v_pk_mul_f32 v[152:153], v[62:63], s[100:101] op_sel_hi:[1,0]
	v_pk_mul_f32 v[154:155], v[64:65], s[100:101] op_sel_hi:[1,0]
	v_pk_mul_f32 v[156:157], v[54:55], s[100:101] op_sel_hi:[1,0]
	v_pk_mul_f32 v[158:159], v[56:57], s[100:101] op_sel_hi:[1,0]
	v_exp_f32_e32 v152, v152
	v_exp_f32_e32 v153, v153
	v_exp_f32_e32 v154, v154
	v_exp_f32_e32 v155, v155
	v_exp_f32_e32 v156, v156
	v_exp_f32_e32 v157, v157
	v_exp_f32_e32 v158, v158
	v_exp_f32_e32 v159, v159
	v_pk_add_f32 v[152:153], v[152:153], 1.0 op_sel_hi:[1,0]
	v_pk_add_f32 v[154:155], v[154:155], 1.0 op_sel_hi:[1,0]
	v_pk_add_f32 v[156:157], v[156:157], 1.0 op_sel_hi:[1,0]
	v_pk_add_f32 v[158:159], v[158:159], 1.0 op_sel_hi:[1,0]
	v_rcp_f32_e32 v152, v152
	v_rcp_f32_e32 v153, v153
	v_rcp_f32_e32 v154, v154
	v_rcp_f32_e32 v155, v155
	v_rcp_f32_e32 v156, v156
	v_rcp_f32_e32 v157, v157
	v_rcp_f32_e32 v158, v158
	v_rcp_f32_e32 v159, v159
	v_pk_mul_f32 v[62:63], v[62:63], v[152:153]
	v_pk_mul_f32 v[64:65], v[64:65], v[154:155]
	v_pk_mul_f32 v[54:55], v[54:55], v[156:157]
	v_pk_mul_f32 v[56:57], v[56:57], v[158:159]
	v_add_u32_e32 v166, 0x80, v146
	v_pk_mul_f32 v[58:59], v[62:63], v[58:59]
	v_pk_mul_f32 v[60:61], v[64:65], v[60:61]
	v_pk_mul_f32 v[50:51], v[54:55], v[50:51]
	v_pk_mul_f32 v[52:53], v[56:57], v[52:53]
	v_mad_i64_i32 v[164:165], s[0:1], v166, s13, v[140:141]
	v_cvt_pk_bf16_f32 v160, v58, v59
	v_cvt_pk_bf16_f32 v161, v60, v61
	v_cvt_pk_bf16_f32 v162, v50, v51
	v_cvt_pk_bf16_f32 v163, v52, v53
	v_lshl_add_u64 v[164:165], v[164:165], 0, v[184:185]
	global_store_dwordx4 v[164:165], v[160:163], off
	v_pk_mul_f32 v[168:169], v[46:47], s[100:101] op_sel_hi:[1,0]
	v_pk_mul_f32 v[170:171], v[48:49], s[100:101] op_sel_hi:[1,0]
	v_pk_mul_f32 v[172:173], v[38:39], s[100:101] op_sel_hi:[1,0]
	v_pk_mul_f32 v[174:175], v[40:41], s[100:101] op_sel_hi:[1,0]
	v_exp_f32_e32 v168, v168
	v_exp_f32_e32 v169, v169
	v_exp_f32_e32 v170, v170
	v_exp_f32_e32 v171, v171
	v_exp_f32_e32 v172, v172
	v_exp_f32_e32 v173, v173
	v_exp_f32_e32 v174, v174
	v_exp_f32_e32 v175, v175
	v_pk_add_f32 v[168:169], v[168:169], 1.0 op_sel_hi:[1,0]
	v_pk_add_f32 v[170:171], v[170:171], 1.0 op_sel_hi:[1,0]
	v_pk_add_f32 v[172:173], v[172:173], 1.0 op_sel_hi:[1,0]
	v_pk_add_f32 v[174:175], v[174:175], 1.0 op_sel_hi:[1,0]
	v_rcp_f32_e32 v168, v168
	v_rcp_f32_e32 v169, v169
	v_rcp_f32_e32 v170, v170
	v_rcp_f32_e32 v171, v171
	v_rcp_f32_e32 v172, v172
	v_rcp_f32_e32 v173, v173
	v_rcp_f32_e32 v174, v174
	v_rcp_f32_e32 v175, v175
	v_pk_mul_f32 v[46:47], v[46:47], v[168:169]
	v_pk_mul_f32 v[48:49], v[48:49], v[170:171]
	v_pk_mul_f32 v[38:39], v[38:39], v[172:173]
	v_pk_mul_f32 v[40:41], v[40:41], v[174:175]
	v_add_u32_e32 v182, 0x90, v146
	v_pk_mul_f32 v[42:43], v[46:47], v[42:43]
	v_pk_mul_f32 v[44:45], v[48:49], v[44:45]
	v_pk_mul_f32 v[34:35], v[38:39], v[34:35]
	v_pk_mul_f32 v[36:37], v[40:41], v[36:37]
	v_mad_i64_i32 v[180:181], s[0:1], v182, s13, v[140:141]
	v_cvt_pk_bf16_f32 v176, v42, v43
	v_cvt_pk_bf16_f32 v177, v44, v45
	v_cvt_pk_bf16_f32 v178, v34, v35
	v_cvt_pk_bf16_f32 v179, v36, v37
	v_lshl_add_u64 v[180:181], v[180:181], 0, v[184:185]
	global_store_dwordx4 v[180:181], v[176:179], off
	v_pk_mul_f32 v[152:153], v[30:31], s[100:101] op_sel_hi:[1,0]
	v_pk_mul_f32 v[154:155], v[32:33], s[100:101] op_sel_hi:[1,0]
	v_pk_mul_f32 v[156:157], v[22:23], s[100:101] op_sel_hi:[1,0]
	v_pk_mul_f32 v[158:159], v[24:25], s[100:101] op_sel_hi:[1,0]
	v_exp_f32_e32 v152, v152
	v_exp_f32_e32 v153, v153
	v_exp_f32_e32 v154, v154
	v_exp_f32_e32 v155, v155
	v_exp_f32_e32 v156, v156
	v_exp_f32_e32 v157, v157
	v_exp_f32_e32 v158, v158
	v_exp_f32_e32 v159, v159
	v_pk_add_f32 v[152:153], v[152:153], 1.0 op_sel_hi:[1,0]
	v_pk_add_f32 v[154:155], v[154:155], 1.0 op_sel_hi:[1,0]
	v_pk_add_f32 v[156:157], v[156:157], 1.0 op_sel_hi:[1,0]
	v_pk_add_f32 v[158:159], v[158:159], 1.0 op_sel_hi:[1,0]
	v_rcp_f32_e32 v152, v152
	v_rcp_f32_e32 v153, v153
	v_rcp_f32_e32 v154, v154
	v_rcp_f32_e32 v155, v155
	v_rcp_f32_e32 v156, v156
	v_rcp_f32_e32 v157, v157
	v_rcp_f32_e32 v158, v158
	v_rcp_f32_e32 v159, v159
	v_pk_mul_f32 v[30:31], v[30:31], v[152:153]
	v_pk_mul_f32 v[32:33], v[32:33], v[154:155]
	v_pk_mul_f32 v[22:23], v[22:23], v[156:157]
	v_pk_mul_f32 v[24:25], v[24:25], v[158:159]
	v_add_u32_e32 v166, 0xa0, v146
	v_pk_mul_f32 v[26:27], v[30:31], v[26:27]
	v_pk_mul_f32 v[28:29], v[32:33], v[28:29]
	v_pk_mul_f32 v[18:19], v[22:23], v[18:19]
	v_pk_mul_f32 v[20:21], v[24:25], v[20:21]
	v_mad_i64_i32 v[164:165], s[0:1], v166, s13, v[140:141]
	v_cvt_pk_bf16_f32 v160, v26, v27
	v_cvt_pk_bf16_f32 v161, v28, v29
	v_cvt_pk_bf16_f32 v162, v18, v19
	v_cvt_pk_bf16_f32 v163, v20, v21
	v_lshl_add_u64 v[164:165], v[164:165], 0, v[184:185]
	global_store_dwordx4 v[164:165], v[160:163], off
	v_pk_mul_f32 v[168:169], v[14:15], s[100:101] op_sel_hi:[1,0]
	v_pk_mul_f32 v[170:171], v[16:17], s[100:101] op_sel_hi:[1,0]
	v_pk_mul_f32 v[172:173], v[6:7], s[100:101] op_sel_hi:[1,0]
	v_pk_mul_f32 v[174:175], v[8:9], s[100:101] op_sel_hi:[1,0]
	v_exp_f32_e32 v168, v168
	v_exp_f32_e32 v169, v169
	v_exp_f32_e32 v170, v170
	v_exp_f32_e32 v171, v171
	v_exp_f32_e32 v172, v172
	v_exp_f32_e32 v173, v173
	v_exp_f32_e32 v174, v174
	v_exp_f32_e32 v175, v175
	v_pk_add_f32 v[168:169], v[168:169], 1.0 op_sel_hi:[1,0]
	v_pk_add_f32 v[170:171], v[170:171], 1.0 op_sel_hi:[1,0]
	v_pk_add_f32 v[172:173], v[172:173], 1.0 op_sel_hi:[1,0]
	v_pk_add_f32 v[174:175], v[174:175], 1.0 op_sel_hi:[1,0]
	v_rcp_f32_e32 v168, v168
	v_rcp_f32_e32 v169, v169
	v_rcp_f32_e32 v170, v170
	v_rcp_f32_e32 v171, v171
	v_rcp_f32_e32 v172, v172
	v_rcp_f32_e32 v173, v173
	v_rcp_f32_e32 v174, v174
	v_rcp_f32_e32 v175, v175
	v_pk_mul_f32 v[14:15], v[14:15], v[168:169]
	v_pk_mul_f32 v[16:17], v[16:17], v[170:171]
	v_pk_mul_f32 v[6:7], v[6:7], v[172:173]
	v_pk_mul_f32 v[8:9], v[8:9], v[174:175]
	v_add_u32_e32 v182, 0xb0, v146
	v_pk_mul_f32 v[10:11], v[14:15], v[10:11]
	v_pk_mul_f32 v[12:13], v[16:17], v[12:13]
	v_pk_mul_f32 v[2:3], v[6:7], v[2:3]
	v_pk_mul_f32 v[4:5], v[8:9], v[4:5]
	v_mad_i64_i32 v[180:181], s[0:1], v182, s13, v[140:141]
	v_cvt_pk_bf16_f32 v176, v10, v11
	v_cvt_pk_bf16_f32 v177, v12, v13
	v_cvt_pk_bf16_f32 v178, v2, v3
	v_cvt_pk_bf16_f32 v179, v4, v5
	v_lshl_add_u64 v[180:181], v[180:181], 0, v[184:185]
	global_store_dwordx4 v[180:181], v[176:179], off
	s_cbranch_vccnz .LBB0_1590
	s_andn2_b64 vcc, exec, s[10:11]
	s_cbranch_vccnz .LBB0_1589
	s_barrier
	s_branch .LBB0_1589
